# GVTF stores nt
# baseline (speedup 1.0000x reference)
.LBB0_186:
	s_mov_b32 s4, 0x3856241d
	v_and_b32_e32 v163, 0x7fffffff, v125
	v_and_b32_e32 v162, 0x7fffffff, v124
	v_mov_b64_e32 v[152:153], s[4:5]
	v_pk_fma_f32 v[164:165], v[162:163], s[94:95], v[152:153] op_sel_hi:[1,0,0]
	v_max_f32_e32 v124, v124, v124
	v_pk_fma_f32 v[164:165], v[162:163], v[164:165], s[96:97] op_sel_hi:[1,1,0]
	v_max_f32_e32 v125, v125, v125
	v_pk_fma_f32 v[164:165], v[162:163], v[164:165], s[98:99] op_sel_hi:[1,1,0]
	v_and_b32_e32 v155, 0x7fffffff, v127
	v_pk_fma_f32 v[164:165], v[162:163], v[164:165], s[40:41] op_sel_hi:[1,1,0]
	v_and_b32_e32 v154, 0x7fffffff, v126
	v_pk_fma_f32 v[164:165], v[162:163], v[164:165], s[74:75] op_sel_hi:[1,1,0]
	v_max_f32_e32 v124, 0, v124
	v_pk_fma_f32 v[164:165], v[162:163], v[164:165], s[76:77] op_sel_hi:[1,1,0]
	v_max_f32_e32 v125, 0, v125
	v_pk_mul_f32 v[164:165], v[164:165], v[164:165]
	v_max_f32_e32 v126, v126, v126
	v_pk_mul_f32 v[164:165], v[164:165], v[164:165]
	v_max_f32_e32 v127, v127, v127
	v_pk_mul_f32 v[164:165], v[164:165], v[164:165]
	v_max_f32_e32 v126, 0, v126
	v_pk_mul_f32 v[164:165], v[164:165], v[164:165]
	v_max_f32_e32 v127, 0, v127
	v_rcp_f32_e32 v164, v164
	v_rcp_f32_e32 v165, v165
	s_lshl_b32 s0, s11, 1
	s_lshl_b32 s82, s86, 1
	s_ashr_i32 s1, s0, 31
	v_pk_fma_f32 v[124:125], v[162:163], v[164:165], v[124:125] neg_lo:[1,0,0] neg_hi:[1,0,0]
	v_pk_fma_f32 v[162:163], v[154:155], s[94:95], v[152:153] op_sel_hi:[1,0,0]
	s_ashr_i32 s83, s82, 31
	v_pk_fma_f32 v[162:163], v[154:155], v[162:163], s[96:97] op_sel_hi:[1,1,0]
	s_lshl_b64 vcc, s[82:83], 8
	v_pk_fma_f32 v[162:163], v[154:155], v[162:163], s[98:99] op_sel_hi:[1,1,0]
	s_lshl_b64 s[4:5], s[0:1], 5
	v_pk_fma_f32 v[162:163], v[154:155], v[162:163], s[40:41] op_sel_hi:[1,1,0]
	s_add_u32 s1, s4, s41
	v_pk_fma_f32 v[162:163], v[154:155], v[162:163], s[74:75] op_sel_hi:[1,1,0]
	s_addc_u32 s11, s5, 0
	v_pk_fma_f32 v[162:163], v[154:155], v[162:163], s[76:77] op_sel_hi:[1,1,0]
	s_add_u32 s12, vcc_lo, s1
	v_pk_mul_f32 v[162:163], v[162:163], v[162:163]
	s_addc_u32 s13, vcc_hi, s11
	v_pk_mul_f32 v[162:163], v[162:163], v[162:163]
	s_nop 0
	v_pk_mul_f32 v[162:163], v[162:163], v[162:163]
	s_nop 0
	v_pk_mul_f32 v[162:163], v[162:163], v[162:163]
	s_nop 0
	v_rcp_f32_e32 v162, v162
	v_rcp_f32_e32 v163, v163
	s_nop 0
	v_pk_fma_f32 v[126:127], v[154:155], v[162:163], v[126:127] neg_lo:[1,0,0] neg_hi:[1,0,0]
	v_and_b32_e32 v163, 0x7fffffff, v121
	v_and_b32_e32 v162, 0x7fffffff, v120
	v_pk_fma_f32 v[164:165], v[162:163], s[94:95], v[152:153] op_sel_hi:[1,0,0]
	v_max_f32_e32 v120, v120, v120
	v_pk_fma_f32 v[164:165], v[162:163], v[164:165], s[96:97] op_sel_hi:[1,1,0]
	v_max_f32_e32 v121, v121, v121
	v_pk_fma_f32 v[164:165], v[162:163], v[164:165], s[98:99] op_sel_hi:[1,1,0]
	v_and_b32_e32 v155, 0x7fffffff, v123
	v_pk_fma_f32 v[164:165], v[162:163], v[164:165], s[40:41] op_sel_hi:[1,1,0]
	v_and_b32_e32 v154, 0x7fffffff, v122
	v_pk_fma_f32 v[164:165], v[162:163], v[164:165], s[74:75] op_sel_hi:[1,1,0]
	v_max_f32_e32 v120, 0, v120
	v_pk_fma_f32 v[164:165], v[162:163], v[164:165], s[76:77] op_sel_hi:[1,1,0]
	v_max_f32_e32 v121, 0, v121
	v_pk_mul_f32 v[164:165], v[164:165], v[164:165]
	v_max_f32_e32 v122, v122, v122
	v_pk_mul_f32 v[164:165], v[164:165], v[164:165]
	v_max_f32_e32 v123, v123, v123
	v_pk_mul_f32 v[164:165], v[164:165], v[164:165]
	v_max_f32_e32 v122, 0, v122
	v_pk_mul_f32 v[164:165], v[164:165], v[164:165]
	v_max_f32_e32 v123, 0, v123
	v_rcp_f32_e32 v164, v164
	v_rcp_f32_e32 v165, v165
	s_nop 0
	v_pk_fma_f32 v[120:121], v[162:163], v[164:165], v[120:121] neg_lo:[1,0,0] neg_hi:[1,0,0]
	v_pk_fma_f32 v[162:163], v[154:155], s[94:95], v[152:153] op_sel_hi:[1,0,0]
	s_nop 0
	v_pk_fma_f32 v[162:163], v[154:155], v[162:163], s[96:97] op_sel_hi:[1,1,0]
	s_nop 0
	v_pk_fma_f32 v[162:163], v[154:155], v[162:163], s[98:99] op_sel_hi:[1,1,0]
	s_nop 0
	v_pk_fma_f32 v[162:163], v[154:155], v[162:163], s[40:41] op_sel_hi:[1,1,0]
	s_nop 0
	v_pk_fma_f32 v[162:163], v[154:155], v[162:163], s[74:75] op_sel_hi:[1,1,0]
	s_nop 0
	v_pk_fma_f32 v[162:163], v[154:155], v[162:163], s[76:77] op_sel_hi:[1,1,0]
	s_nop 0
	v_pk_mul_f32 v[162:163], v[162:163], v[162:163]
	s_nop 0
	v_pk_mul_f32 v[162:163], v[162:163], v[162:163]
	s_nop 0
	v_pk_mul_f32 v[162:163], v[162:163], v[162:163]
	s_nop 0
	v_pk_mul_f32 v[162:163], v[162:163], v[162:163]
	s_nop 0
	v_rcp_f32_e32 v162, v162
	v_rcp_f32_e32 v163, v163
	s_nop 0
	v_pk_fma_f32 v[122:123], v[154:155], v[162:163], v[122:123] neg_lo:[1,0,0] neg_hi:[1,0,0]
	v_mov_b32_e32 v155, s13
	v_or_b32_e32 v154, s12, v138
	v_lshlrev_b64 v[154:155], 10, v[154:155]
	v_cvt_pk_bf16_f32 v162, v124, v125
	v_cvt_pk_bf16_f32 v163, v126, v127
	v_cvt_pk_bf16_f32 v164, v120, v121
	v_cvt_pk_bf16_f32 v165, v122, v123
	v_lshl_add_u64 v[154:155], v[142:143], 0, v[154:155]
	global_store_dwordx4 v[154:155], v[162:165], off nt
	s_or_b32 s12, s82, 1
	s_ashr_i32 s13, s12, 31
	v_and_b32_e32 v165, 0x7fffffff, v117
	v_and_b32_e32 v164, 0x7fffffff, v116
	v_pk_fma_f32 v[166:167], v[164:165], s[94:95], v[152:153] op_sel_hi:[1,0,0]
	v_max_f32_e32 v116, v116, v116
	v_pk_fma_f32 v[166:167], v[164:165], v[166:167], s[96:97] op_sel_hi:[1,1,0]
	v_max_f32_e32 v117, v117, v117
	v_pk_fma_f32 v[166:167], v[164:165], v[166:167], s[98:99] op_sel_hi:[1,1,0]
	v_and_b32_e32 v163, 0x7fffffff, v119
	v_pk_fma_f32 v[166:167], v[164:165], v[166:167], s[40:41] op_sel_hi:[1,1,0]
	v_and_b32_e32 v162, 0x7fffffff, v118
	v_pk_fma_f32 v[166:167], v[164:165], v[166:167], s[74:75] op_sel_hi:[1,1,0]
	v_max_f32_e32 v116, 0, v116
	v_pk_fma_f32 v[166:167], v[164:165], v[166:167], s[76:77] op_sel_hi:[1,1,0]
	v_max_f32_e32 v117, 0, v117
	v_pk_mul_f32 v[166:167], v[166:167], v[166:167]
	v_max_f32_e32 v118, v118, v118
	v_pk_mul_f32 v[166:167], v[166:167], v[166:167]
	v_max_f32_e32 v119, v119, v119
	v_pk_mul_f32 v[166:167], v[166:167], v[166:167]
	v_max_f32_e32 v118, 0, v118
	v_pk_mul_f32 v[166:167], v[166:167], v[166:167]
	v_max_f32_e32 v119, 0, v119
	v_rcp_f32_e32 v166, v166
	v_rcp_f32_e32 v167, v167
	s_lshl_b64 s[82:83], s[12:13], 8
	s_add_u32 s1, s82, s1
	s_addc_u32 s11, s83, s11
	v_pk_fma_f32 v[116:117], v[164:165], v[166:167], v[116:117] neg_lo:[1,0,0] neg_hi:[1,0,0]
	v_pk_fma_f32 v[164:165], v[162:163], s[94:95], v[152:153] op_sel_hi:[1,0,0]
	s_nop 0
	v_pk_fma_f32 v[164:165], v[162:163], v[164:165], s[96:97] op_sel_hi:[1,1,0]
	s_nop 0
	v_pk_fma_f32 v[164:165], v[162:163], v[164:165], s[98:99] op_sel_hi:[1,1,0]
	s_nop 0
	v_pk_fma_f32 v[164:165], v[162:163], v[164:165], s[40:41] op_sel_hi:[1,1,0]
	s_nop 0
	v_pk_fma_f32 v[164:165], v[162:163], v[164:165], s[74:75] op_sel_hi:[1,1,0]
	s_nop 0
	v_pk_fma_f32 v[164:165], v[162:163], v[164:165], s[76:77] op_sel_hi:[1,1,0]
	s_nop 0
	v_pk_mul_f32 v[164:165], v[164:165], v[164:165]
	s_nop 0
	v_pk_mul_f32 v[164:165], v[164:165], v[164:165]
	s_nop 0
	v_pk_mul_f32 v[164:165], v[164:165], v[164:165]
	s_nop 0
	v_pk_mul_f32 v[164:165], v[164:165], v[164:165]
	s_nop 0
	v_rcp_f32_e32 v164, v164
	v_rcp_f32_e32 v165, v165
	s_nop 0
	v_pk_fma_f32 v[118:119], v[162:163], v[164:165], v[118:119] neg_lo:[1,0,0] neg_hi:[1,0,0]
	v_and_b32_e32 v165, 0x7fffffff, v113
	v_and_b32_e32 v164, 0x7fffffff, v112
	v_pk_fma_f32 v[166:167], v[164:165], s[94:95], v[152:153] op_sel_hi:[1,0,0]
	v_max_f32_e32 v112, v112, v112
	v_pk_fma_f32 v[166:167], v[164:165], v[166:167], s[96:97] op_sel_hi:[1,1,0]
	v_max_f32_e32 v113, v113, v113
	v_pk_fma_f32 v[166:167], v[164:165], v[166:167], s[98:99] op_sel_hi:[1,1,0]
	v_and_b32_e32 v163, 0x7fffffff, v115
	v_pk_fma_f32 v[166:167], v[164:165], v[166:167], s[40:41] op_sel_hi:[1,1,0]
	v_and_b32_e32 v162, 0x7fffffff, v114
	v_pk_fma_f32 v[166:167], v[164:165], v[166:167], s[74:75] op_sel_hi:[1,1,0]
	v_max_f32_e32 v112, 0, v112
	v_pk_fma_f32 v[166:167], v[164:165], v[166:167], s[76:77] op_sel_hi:[1,1,0]
	v_max_f32_e32 v113, 0, v113
	v_pk_mul_f32 v[166:167], v[166:167], v[166:167]
	v_max_f32_e32 v114, v114, v114
	v_pk_mul_f32 v[166:167], v[166:167], v[166:167]
	v_max_f32_e32 v115, v115, v115
	v_pk_mul_f32 v[166:167], v[166:167], v[166:167]
	v_max_f32_e32 v114, 0, v114
	v_pk_mul_f32 v[166:167], v[166:167], v[166:167]
	v_max_f32_e32 v115, 0, v115
	v_rcp_f32_e32 v166, v166
	v_rcp_f32_e32 v167, v167
	s_nop 0
	v_pk_fma_f32 v[112:113], v[164:165], v[166:167], v[112:113] neg_lo:[1,0,0] neg_hi:[1,0,0]
	v_pk_fma_f32 v[164:165], v[162:163], s[94:95], v[152:153] op_sel_hi:[1,0,0]
	v_mov_b32_e32 v167, s11
	v_pk_fma_f32 v[164:165], v[162:163], v[164:165], s[96:97] op_sel_hi:[1,1,0]
	v_or_b32_e32 v166, s1, v138
	v_pk_fma_f32 v[164:165], v[162:163], v[164:165], s[98:99] op_sel_hi:[1,1,0]
	v_lshlrev_b64 v[166:167], 10, v[166:167]
	v_pk_fma_f32 v[164:165], v[162:163], v[164:165], s[40:41] op_sel_hi:[1,1,0]
	v_lshl_add_u64 v[166:167], v[142:143], 0, v[166:167]
	v_pk_fma_f32 v[164:165], v[162:163], v[164:165], s[74:75] op_sel_hi:[1,1,0]
	s_add_u32 s1, s4, s6
	v_pk_fma_f32 v[164:165], v[162:163], v[164:165], s[76:77] op_sel_hi:[1,1,0]
	s_addc_u32 s4, s5, 0
	v_pk_mul_f32 v[164:165], v[164:165], v[164:165]
	s_add_u32 s5, vcc_lo, s1
	v_pk_mul_f32 v[164:165], v[164:165], v[164:165]
	s_addc_u32 s11, vcc_hi, s4
	v_pk_mul_f32 v[164:165], v[164:165], v[164:165]
	s_add_u32 s1, s82, s1
	v_pk_mul_f32 v[164:165], v[164:165], v[164:165]
	s_addc_u32 s4, s83, s4
	v_rcp_f32_e32 v164, v164
	v_rcp_f32_e32 v165, v165
	s_or_b32 s0, s0, 1
	v_pk_fma_f32 v[114:115], v[162:163], v[164:165], v[114:115] neg_lo:[1,0,0] neg_hi:[1,0,0]
	v_cvt_pk_bf16_f32 v162, v116, v117
	v_cvt_pk_bf16_f32 v163, v118, v119
	v_cvt_pk_bf16_f32 v164, v112, v113
	s_nop 0
	v_cvt_pk_bf16_f32 v165, v114, v115
	global_store_dwordx4 v[166:167], v[162:165], off nt
	s_nop 1
	v_and_b32_e32 v165, 0x7fffffff, v109
	v_and_b32_e32 v164, 0x7fffffff, v108
	v_pk_fma_f32 v[168:169], v[164:165], s[94:95], v[152:153] op_sel_hi:[1,0,0]
	v_max_f32_e32 v108, v108, v108
	v_pk_fma_f32 v[168:169], v[164:165], v[168:169], s[96:97] op_sel_hi:[1,1,0]
	v_max_f32_e32 v109, v109, v109
	v_pk_fma_f32 v[168:169], v[164:165], v[168:169], s[98:99] op_sel_hi:[1,1,0]
	v_and_b32_e32 v163, 0x7fffffff, v111
	v_pk_fma_f32 v[168:169], v[164:165], v[168:169], s[40:41] op_sel_hi:[1,1,0]
	v_and_b32_e32 v162, 0x7fffffff, v110
	v_pk_fma_f32 v[168:169], v[164:165], v[168:169], s[74:75] op_sel_hi:[1,1,0]
	v_max_f32_e32 v108, 0, v108
	v_pk_fma_f32 v[168:169], v[164:165], v[168:169], s[76:77] op_sel_hi:[1,1,0]
	v_max_f32_e32 v109, 0, v109
	v_pk_mul_f32 v[168:169], v[168:169], v[168:169]
	v_max_f32_e32 v110, v110, v110
	v_pk_mul_f32 v[168:169], v[168:169], v[168:169]
	v_max_f32_e32 v111, v111, v111
	v_pk_mul_f32 v[168:169], v[168:169], v[168:169]
	v_max_f32_e32 v110, 0, v110
	v_pk_mul_f32 v[168:169], v[168:169], v[168:169]
	v_max_f32_e32 v111, 0, v111
	v_rcp_f32_e32 v168, v168
	v_rcp_f32_e32 v169, v169
	s_nop 0
	v_pk_fma_f32 v[108:109], v[164:165], v[168:169], v[108:109] neg_lo:[1,0,0] neg_hi:[1,0,0]
	v_pk_fma_f32 v[164:165], v[162:163], s[94:95], v[152:153] op_sel_hi:[1,0,0]
	s_nop 0
	v_pk_fma_f32 v[164:165], v[162:163], v[164:165], s[96:97] op_sel_hi:[1,1,0]
	s_nop 0
	v_pk_fma_f32 v[164:165], v[162:163], v[164:165], s[98:99] op_sel_hi:[1,1,0]
	s_nop 0
	v_pk_fma_f32 v[164:165], v[162:163], v[164:165], s[40:41] op_sel_hi:[1,1,0]
	s_nop 0
	v_pk_fma_f32 v[164:165], v[162:163], v[164:165], s[74:75] op_sel_hi:[1,1,0]
	s_nop 0
	v_pk_fma_f32 v[164:165], v[162:163], v[164:165], s[76:77] op_sel_hi:[1,1,0]
	s_nop 0
	v_pk_mul_f32 v[164:165], v[164:165], v[164:165]
	s_nop 0
	v_pk_mul_f32 v[164:165], v[164:165], v[164:165]
	s_nop 0
	v_pk_mul_f32 v[164:165], v[164:165], v[164:165]
	s_nop 0
	v_pk_mul_f32 v[164:165], v[164:165], v[164:165]
	s_nop 0
	v_rcp_f32_e32 v164, v164
	v_rcp_f32_e32 v165, v165
	s_nop 0
	v_pk_fma_f32 v[110:111], v[162:163], v[164:165], v[110:111] neg_lo:[1,0,0] neg_hi:[1,0,0]
	v_and_b32_e32 v165, 0x7fffffff, v105
	v_and_b32_e32 v164, 0x7fffffff, v104
	v_pk_fma_f32 v[168:169], v[164:165], s[94:95], v[152:153] op_sel_hi:[1,0,0]
	v_max_f32_e32 v104, v104, v104
	v_pk_fma_f32 v[168:169], v[164:165], v[168:169], s[96:97] op_sel_hi:[1,1,0]
	v_max_f32_e32 v105, v105, v105
	v_pk_fma_f32 v[168:169], v[164:165], v[168:169], s[98:99] op_sel_hi:[1,1,0]
	v_and_b32_e32 v163, 0x7fffffff, v107
	v_pk_fma_f32 v[168:169], v[164:165], v[168:169], s[40:41] op_sel_hi:[1,1,0]
	v_and_b32_e32 v162, 0x7fffffff, v106
	v_pk_fma_f32 v[168:169], v[164:165], v[168:169], s[74:75] op_sel_hi:[1,1,0]
	v_max_f32_e32 v104, 0, v104
	v_pk_fma_f32 v[168:169], v[164:165], v[168:169], s[76:77] op_sel_hi:[1,1,0]
	v_max_f32_e32 v105, 0, v105
	v_pk_mul_f32 v[168:169], v[168:169], v[168:169]
	v_max_f32_e32 v106, v106, v106
	v_pk_mul_f32 v[168:169], v[168:169], v[168:169]
	v_max_f32_e32 v107, v107, v107
	v_pk_mul_f32 v[168:169], v[168:169], v[168:169]
	v_max_f32_e32 v106, 0, v106
	v_pk_mul_f32 v[168:169], v[168:169], v[168:169]
	v_max_f32_e32 v107, 0, v107
	v_rcp_f32_e32 v168, v168
	v_rcp_f32_e32 v169, v169
	s_nop 0
	v_pk_fma_f32 v[164:165], v[164:165], v[168:169], v[104:105] neg_lo:[1,0,0] neg_hi:[1,0,0]
	v_pk_fma_f32 v[104:105], v[162:163], s[94:95], v[152:153] op_sel_hi:[1,0,0]
	s_nop 0
	v_pk_fma_f32 v[104:105], v[162:163], v[104:105], s[96:97] op_sel_hi:[1,1,0]
	s_nop 0
	v_pk_fma_f32 v[104:105], v[162:163], v[104:105], s[98:99] op_sel_hi:[1,1,0]
	s_nop 0
	v_pk_fma_f32 v[104:105], v[162:163], v[104:105], s[40:41] op_sel_hi:[1,1,0]
	s_nop 0
	v_pk_fma_f32 v[104:105], v[162:163], v[104:105], s[74:75] op_sel_hi:[1,1,0]
	s_nop 0
	v_pk_fma_f32 v[104:105], v[162:163], v[104:105], s[76:77] op_sel_hi:[1,1,0]
	s_nop 0
	v_pk_mul_f32 v[104:105], v[104:105], v[104:105]
	s_nop 0
	v_pk_mul_f32 v[104:105], v[104:105], v[104:105]
	s_nop 0
	v_pk_mul_f32 v[104:105], v[104:105], v[104:105]
	s_nop 0
	v_pk_mul_f32 v[104:105], v[104:105], v[104:105]
	s_nop 0
	v_rcp_f32_e32 v104, v104
	v_rcp_f32_e32 v105, v105
	s_nop 0
	v_pk_fma_f32 v[162:163], v[162:163], v[104:105], v[106:107] neg_lo:[1,0,0] neg_hi:[1,0,0]
	v_pk_mul_f32 v[104:105], v[108:109], v[108:109]
	s_nop 0
	v_pk_fma_f32 v[124:125], v[124:125], v[124:125], v[104:105]
	v_pk_mul_f32 v[104:105], v[164:165], v[164:165]
	s_nop 0
	v_pk_fma_f32 v[120:121], v[120:121], v[120:121], v[104:105]
	v_pk_mul_f32 v[104:105], v[110:111], v[110:111]
	s_nop 0
	v_pk_fma_f32 v[126:127], v[126:127], v[126:127], v[104:105]
	v_pk_mul_f32 v[104:105], v[162:163], v[162:163]
	s_nop 0
	v_pk_fma_f32 v[122:123], v[122:123], v[122:123], v[104:105]
	v_cvt_pk_bf16_f32 v104, v108, v109
	v_cvt_pk_bf16_f32 v105, v110, v111
	v_cvt_pk_bf16_f32 v106, v164, v165
	v_cvt_pk_bf16_f32 v107, v162, v163
	global_store_dwordx4 v[154:155], v[104:107], off offset:128 nt
	s_nop 1
	v_and_b32_e32 v107, 0x7fffffff, v101
	v_and_b32_e32 v106, 0x7fffffff, v100
	v_pk_fma_f32 v[108:109], v[106:107], s[94:95], v[152:153] op_sel_hi:[1,0,0]
	v_max_f32_e32 v100, v100, v100
	v_pk_fma_f32 v[108:109], v[106:107], v[108:109], s[96:97] op_sel_hi:[1,1,0]
	v_max_f32_e32 v101, v101, v101
	v_pk_fma_f32 v[108:109], v[106:107], v[108:109], s[98:99] op_sel_hi:[1,1,0]
	v_and_b32_e32 v105, 0x7fffffff, v103
	v_pk_fma_f32 v[108:109], v[106:107], v[108:109], s[40:41] op_sel_hi:[1,1,0]
	v_and_b32_e32 v104, 0x7fffffff, v102
	v_pk_fma_f32 v[108:109], v[106:107], v[108:109], s[74:75] op_sel_hi:[1,1,0]
	v_max_f32_e32 v100, 0, v100
	v_pk_fma_f32 v[108:109], v[106:107], v[108:109], s[76:77] op_sel_hi:[1,1,0]
	v_max_f32_e32 v101, 0, v101
	v_pk_mul_f32 v[108:109], v[108:109], v[108:109]
	v_max_f32_e32 v102, v102, v102
	v_pk_mul_f32 v[108:109], v[108:109], v[108:109]
	v_max_f32_e32 v103, v103, v103
	v_pk_mul_f32 v[108:109], v[108:109], v[108:109]
	v_max_f32_e32 v102, 0, v102
	v_pk_mul_f32 v[108:109], v[108:109], v[108:109]
	v_max_f32_e32 v103, 0, v103
	v_rcp_f32_e32 v108, v108
	v_rcp_f32_e32 v109, v109
	s_nop 0
	v_pk_fma_f32 v[100:101], v[106:107], v[108:109], v[100:101] neg_lo:[1,0,0] neg_hi:[1,0,0]
	v_pk_fma_f32 v[106:107], v[104:105], s[94:95], v[152:153] op_sel_hi:[1,0,0]
	s_nop 0
	v_pk_fma_f32 v[106:107], v[104:105], v[106:107], s[96:97] op_sel_hi:[1,1,0]
	s_nop 0
	v_pk_fma_f32 v[106:107], v[104:105], v[106:107], s[98:99] op_sel_hi:[1,1,0]
	s_nop 0
	v_pk_fma_f32 v[106:107], v[104:105], v[106:107], s[40:41] op_sel_hi:[1,1,0]
	s_nop 0
	v_pk_fma_f32 v[106:107], v[104:105], v[106:107], s[74:75] op_sel_hi:[1,1,0]
	s_nop 0
	v_pk_fma_f32 v[106:107], v[104:105], v[106:107], s[76:77] op_sel_hi:[1,1,0]
	s_nop 0
	v_pk_mul_f32 v[106:107], v[106:107], v[106:107]
	s_nop 0
	v_pk_mul_f32 v[106:107], v[106:107], v[106:107]
	s_nop 0
	v_pk_mul_f32 v[106:107], v[106:107], v[106:107]
	s_nop 0
	v_pk_mul_f32 v[106:107], v[106:107], v[106:107]
	s_nop 0
	v_rcp_f32_e32 v106, v106
	v_rcp_f32_e32 v107, v107
	s_nop 0
	v_pk_fma_f32 v[102:103], v[104:105], v[106:107], v[102:103] neg_lo:[1,0,0] neg_hi:[1,0,0]
	v_and_b32_e32 v107, 0x7fffffff, v97
	v_and_b32_e32 v106, 0x7fffffff, v96
	v_pk_fma_f32 v[108:109], v[106:107], s[94:95], v[152:153] op_sel_hi:[1,0,0]
	v_max_f32_e32 v96, v96, v96
	v_pk_fma_f32 v[108:109], v[106:107], v[108:109], s[96:97] op_sel_hi:[1,1,0]
	v_max_f32_e32 v97, v97, v97
	v_pk_fma_f32 v[108:109], v[106:107], v[108:109], s[98:99] op_sel_hi:[1,1,0]
	v_and_b32_e32 v105, 0x7fffffff, v99
	v_pk_fma_f32 v[108:109], v[106:107], v[108:109], s[40:41] op_sel_hi:[1,1,0]
	v_and_b32_e32 v104, 0x7fffffff, v98
	v_pk_fma_f32 v[108:109], v[106:107], v[108:109], s[74:75] op_sel_hi:[1,1,0]
	v_max_f32_e32 v96, 0, v96
	v_pk_fma_f32 v[108:109], v[106:107], v[108:109], s[76:77] op_sel_hi:[1,1,0]
	v_max_f32_e32 v97, 0, v97
	v_pk_mul_f32 v[108:109], v[108:109], v[108:109]
	v_max_f32_e32 v98, v98, v98
	v_pk_mul_f32 v[108:109], v[108:109], v[108:109]
	v_max_f32_e32 v99, v99, v99
	v_pk_mul_f32 v[108:109], v[108:109], v[108:109]
	v_max_f32_e32 v98, 0, v98
	v_pk_mul_f32 v[108:109], v[108:109], v[108:109]
	v_max_f32_e32 v99, 0, v99
	v_rcp_f32_e32 v108, v108
	v_rcp_f32_e32 v109, v109
	s_nop 0
	v_pk_fma_f32 v[106:107], v[106:107], v[108:109], v[96:97] neg_lo:[1,0,0] neg_hi:[1,0,0]
	v_pk_fma_f32 v[96:97], v[104:105], s[94:95], v[152:153] op_sel_hi:[1,0,0]
	s_nop 0
	v_pk_fma_f32 v[96:97], v[104:105], v[96:97], s[96:97] op_sel_hi:[1,1,0]
	s_nop 0
	v_pk_fma_f32 v[96:97], v[104:105], v[96:97], s[98:99] op_sel_hi:[1,1,0]
	s_nop 0
	v_pk_fma_f32 v[96:97], v[104:105], v[96:97], s[40:41] op_sel_hi:[1,1,0]
	s_nop 0
	v_pk_fma_f32 v[96:97], v[104:105], v[96:97], s[74:75] op_sel_hi:[1,1,0]
	s_nop 0
	v_pk_fma_f32 v[96:97], v[104:105], v[96:97], s[76:77] op_sel_hi:[1,1,0]
	s_nop 0
	v_pk_mul_f32 v[96:97], v[96:97], v[96:97]
	s_nop 0
	v_pk_mul_f32 v[96:97], v[96:97], v[96:97]
	s_nop 0
	v_pk_mul_f32 v[96:97], v[96:97], v[96:97]
	s_nop 0
	v_pk_mul_f32 v[96:97], v[96:97], v[96:97]
	s_nop 0
	v_rcp_f32_e32 v96, v96
	v_rcp_f32_e32 v97, v97
	s_nop 0
	v_pk_fma_f32 v[104:105], v[104:105], v[96:97], v[98:99] neg_lo:[1,0,0] neg_hi:[1,0,0]
	v_pk_mul_f32 v[98:99], v[106:107], v[106:107]
	v_pk_mul_f32 v[96:97], v[100:101], v[100:101]
	v_pk_fma_f32 v[108:109], v[112:113], v[112:113], v[98:99]
	v_pk_mul_f32 v[98:99], v[102:103], v[102:103]
	v_pk_fma_f32 v[96:97], v[116:117], v[116:117], v[96:97]
	v_pk_fma_f32 v[110:111], v[118:119], v[118:119], v[98:99]
	v_pk_mul_f32 v[98:99], v[104:105], v[104:105]
	s_nop 0
	v_pk_fma_f32 v[112:113], v[114:115], v[114:115], v[98:99]
	v_cvt_pk_bf16_f32 v98, v100, v101
	v_cvt_pk_bf16_f32 v99, v102, v103
	v_cvt_pk_bf16_f32 v100, v106, v107
	v_cvt_pk_bf16_f32 v101, v104, v105
	global_store_dwordx4 v[166:167], v[98:101], off offset:128 nt
	s_nop 1
	v_and_b32_e32 v101, 0x7fffffff, v93
	v_and_b32_e32 v100, 0x7fffffff, v92
	v_pk_fma_f32 v[102:103], v[100:101], s[94:95], v[152:153] op_sel_hi:[1,0,0]
	v_max_f32_e32 v92, v92, v92
	v_pk_fma_f32 v[102:103], v[100:101], v[102:103], s[96:97] op_sel_hi:[1,1,0]
	v_max_f32_e32 v93, v93, v93
	v_pk_fma_f32 v[102:103], v[100:101], v[102:103], s[98:99] op_sel_hi:[1,1,0]
	v_and_b32_e32 v99, 0x7fffffff, v95
	v_pk_fma_f32 v[102:103], v[100:101], v[102:103], s[40:41] op_sel_hi:[1,1,0]
	v_and_b32_e32 v98, 0x7fffffff, v94
	v_pk_fma_f32 v[102:103], v[100:101], v[102:103], s[74:75] op_sel_hi:[1,1,0]
	v_max_f32_e32 v92, 0, v92
	v_pk_fma_f32 v[102:103], v[100:101], v[102:103], s[76:77] op_sel_hi:[1,1,0]
	v_max_f32_e32 v93, 0, v93
	v_pk_mul_f32 v[102:103], v[102:103], v[102:103]
	v_max_f32_e32 v94, v94, v94
	v_pk_mul_f32 v[102:103], v[102:103], v[102:103]
	v_max_f32_e32 v95, v95, v95
	v_pk_mul_f32 v[102:103], v[102:103], v[102:103]
	v_max_f32_e32 v94, 0, v94
	v_pk_mul_f32 v[102:103], v[102:103], v[102:103]
	v_max_f32_e32 v95, 0, v95
	v_rcp_f32_e32 v102, v102
	v_rcp_f32_e32 v103, v103
	s_nop 0
	v_pk_fma_f32 v[100:101], v[100:101], v[102:103], v[92:93] neg_lo:[1,0,0] neg_hi:[1,0,0]
	v_pk_fma_f32 v[92:93], v[98:99], s[94:95], v[152:153] op_sel_hi:[1,0,0]
	s_nop 0
	v_pk_fma_f32 v[92:93], v[98:99], v[92:93], s[96:97] op_sel_hi:[1,1,0]
	s_nop 0
	v_pk_fma_f32 v[92:93], v[98:99], v[92:93], s[98:99] op_sel_hi:[1,1,0]
	s_nop 0
	v_pk_fma_f32 v[92:93], v[98:99], v[92:93], s[40:41] op_sel_hi:[1,1,0]
	s_nop 0
	v_pk_fma_f32 v[92:93], v[98:99], v[92:93], s[74:75] op_sel_hi:[1,1,0]
	s_nop 0
	v_pk_fma_f32 v[92:93], v[98:99], v[92:93], s[76:77] op_sel_hi:[1,1,0]
	s_nop 0
	v_pk_mul_f32 v[92:93], v[92:93], v[92:93]
	s_nop 0
	v_pk_mul_f32 v[92:93], v[92:93], v[92:93]
	s_nop 0
	v_pk_mul_f32 v[92:93], v[92:93], v[92:93]
	s_nop 0
	v_pk_mul_f32 v[92:93], v[92:93], v[92:93]
	s_nop 0
	v_rcp_f32_e32 v92, v92
	v_rcp_f32_e32 v93, v93
	s_nop 0
	v_pk_fma_f32 v[102:103], v[98:99], v[92:93], v[94:95] neg_lo:[1,0,0] neg_hi:[1,0,0]
	v_and_b32_e32 v95, 0x7fffffff, v89
	v_and_b32_e32 v94, 0x7fffffff, v88
	v_pk_fma_f32 v[98:99], v[94:95], s[94:95], v[152:153] op_sel_hi:[1,0,0]
	v_max_f32_e32 v88, v88, v88
	v_pk_fma_f32 v[98:99], v[94:95], v[98:99], s[96:97] op_sel_hi:[1,1,0]
	v_max_f32_e32 v89, v89, v89
	v_pk_fma_f32 v[98:99], v[94:95], v[98:99], s[98:99] op_sel_hi:[1,1,0]
	v_and_b32_e32 v93, 0x7fffffff, v91
	v_pk_fma_f32 v[98:99], v[94:95], v[98:99], s[40:41] op_sel_hi:[1,1,0]
	v_and_b32_e32 v92, 0x7fffffff, v90
	v_pk_fma_f32 v[98:99], v[94:95], v[98:99], s[74:75] op_sel_hi:[1,1,0]
	v_max_f32_e32 v88, 0, v88
	v_pk_fma_f32 v[98:99], v[94:95], v[98:99], s[76:77] op_sel_hi:[1,1,0]
	v_max_f32_e32 v89, 0, v89
	v_pk_mul_f32 v[98:99], v[98:99], v[98:99]
	v_max_f32_e32 v90, v90, v90
	v_pk_mul_f32 v[98:99], v[98:99], v[98:99]
	v_max_f32_e32 v91, v91, v91
	v_pk_mul_f32 v[98:99], v[98:99], v[98:99]
	v_max_f32_e32 v90, 0, v90
	v_pk_mul_f32 v[98:99], v[98:99], v[98:99]
	v_max_f32_e32 v91, 0, v91
	v_rcp_f32_e32 v98, v98
	v_rcp_f32_e32 v99, v99
	s_nop 0
	v_pk_fma_f32 v[104:105], v[94:95], v[98:99], v[88:89] neg_lo:[1,0,0] neg_hi:[1,0,0]
	v_pk_fma_f32 v[88:89], v[92:93], s[94:95], v[152:153] op_sel_hi:[1,0,0]
	v_cvt_pk_bf16_f32 v98, v100, v101
	v_cvt_pk_bf16_f32 v99, v102, v103
	s_nop 0
	v_pk_fma_f32 v[88:89], v[92:93], v[88:89], s[96:97] op_sel_hi:[1,1,0]
	s_nop 0
	v_pk_fma_f32 v[88:89], v[92:93], v[88:89], s[98:99] op_sel_hi:[1,1,0]
	s_nop 0
	v_pk_fma_f32 v[88:89], v[92:93], v[88:89], s[40:41] op_sel_hi:[1,1,0]
	s_nop 0
	v_pk_fma_f32 v[88:89], v[92:93], v[88:89], s[74:75] op_sel_hi:[1,1,0]
	s_nop 0
	v_pk_fma_f32 v[88:89], v[92:93], v[88:89], s[76:77] op_sel_hi:[1,1,0]
	s_nop 0
	v_pk_mul_f32 v[88:89], v[88:89], v[88:89]
	s_nop 0
	v_pk_mul_f32 v[88:89], v[88:89], v[88:89]
	s_nop 0
	v_pk_mul_f32 v[88:89], v[88:89], v[88:89]
	s_nop 0
	v_pk_mul_f32 v[88:89], v[88:89], v[88:89]
	s_nop 0
	v_rcp_f32_e32 v88, v88
	v_rcp_f32_e32 v89, v89
	s_nop 0
	v_pk_fma_f32 v[106:107], v[92:93], v[88:89], v[90:91] neg_lo:[1,0,0] neg_hi:[1,0,0]
	v_pk_fma_f32 v[92:93], v[102:103], v[102:103], v[126:127]
	v_mov_b32_e32 v103, s11
	v_or_b32_e32 v102, s5, v138
	v_lshlrev_b64 v[102:103], 10, v[102:103]
	v_pk_fma_f32 v[88:89], v[100:101], v[100:101], v[124:125]
	v_cvt_pk_bf16_f32 v100, v104, v105
	v_cvt_pk_bf16_f32 v101, v106, v107
	v_lshl_add_u64 v[102:103], v[142:143], 0, v[102:103]
	global_store_dwordx4 v[102:103], v[98:101], off nt
	v_pk_fma_f32 v[90:91], v[104:105], v[104:105], v[120:121]
	v_pk_fma_f32 v[94:95], v[106:107], v[106:107], v[122:123]
	v_and_b32_e32 v101, 0x7fffffff, v85
	v_and_b32_e32 v100, 0x7fffffff, v84
	v_pk_fma_f32 v[104:105], v[100:101], s[94:95], v[152:153] op_sel_hi:[1,0,0]
	v_max_f32_e32 v84, v84, v84
	v_pk_fma_f32 v[104:105], v[100:101], v[104:105], s[96:97] op_sel_hi:[1,1,0]
	v_max_f32_e32 v85, v85, v85
	v_pk_fma_f32 v[104:105], v[100:101], v[104:105], s[98:99] op_sel_hi:[1,1,0]
	v_and_b32_e32 v99, 0x7fffffff, v87
	v_pk_fma_f32 v[104:105], v[100:101], v[104:105], s[40:41] op_sel_hi:[1,1,0]
	v_and_b32_e32 v98, 0x7fffffff, v86
	v_pk_fma_f32 v[104:105], v[100:101], v[104:105], s[74:75] op_sel_hi:[1,1,0]
	v_max_f32_e32 v84, 0, v84
	v_pk_fma_f32 v[104:105], v[100:101], v[104:105], s[76:77] op_sel_hi:[1,1,0]
	v_max_f32_e32 v85, 0, v85
	v_pk_mul_f32 v[104:105], v[104:105], v[104:105]
	v_max_f32_e32 v86, v86, v86
	v_pk_mul_f32 v[104:105], v[104:105], v[104:105]
	v_max_f32_e32 v87, v87, v87
	v_pk_mul_f32 v[104:105], v[104:105], v[104:105]
	v_max_f32_e32 v86, 0, v86
	v_pk_mul_f32 v[104:105], v[104:105], v[104:105]
	v_max_f32_e32 v87, 0, v87
	v_rcp_f32_e32 v104, v104
	v_rcp_f32_e32 v105, v105
	s_nop 0
	v_pk_fma_f32 v[84:85], v[100:101], v[104:105], v[84:85] neg_lo:[1,0,0] neg_hi:[1,0,0]
	v_pk_fma_f32 v[100:101], v[98:99], s[94:95], v[152:153] op_sel_hi:[1,0,0]
	v_pk_fma_f32 v[96:97], v[84:85], v[84:85], v[96:97]
	v_pk_fma_f32 v[100:101], v[98:99], v[100:101], s[96:97] op_sel_hi:[1,1,0]
	s_nop 0
	v_pk_fma_f32 v[100:101], v[98:99], v[100:101], s[98:99] op_sel_hi:[1,1,0]
	s_nop 0
	v_pk_fma_f32 v[100:101], v[98:99], v[100:101], s[40:41] op_sel_hi:[1,1,0]
	s_nop 0
	v_pk_fma_f32 v[100:101], v[98:99], v[100:101], s[74:75] op_sel_hi:[1,1,0]
	s_nop 0
	v_pk_fma_f32 v[100:101], v[98:99], v[100:101], s[76:77] op_sel_hi:[1,1,0]
	s_nop 0
	v_pk_mul_f32 v[100:101], v[100:101], v[100:101]
	s_nop 0
	v_pk_mul_f32 v[100:101], v[100:101], v[100:101]
	s_nop 0
	v_pk_mul_f32 v[100:101], v[100:101], v[100:101]
	s_nop 0
	v_pk_mul_f32 v[100:101], v[100:101], v[100:101]
	s_nop 0
	v_rcp_f32_e32 v100, v100
	v_rcp_f32_e32 v101, v101
	s_nop 0
	v_pk_fma_f32 v[86:87], v[98:99], v[100:101], v[86:87] neg_lo:[1,0,0] neg_hi:[1,0,0]
	v_and_b32_e32 v101, 0x7fffffff, v81
	v_and_b32_e32 v100, 0x7fffffff, v80
	v_pk_fma_f32 v[104:105], v[100:101], s[94:95], v[152:153] op_sel_hi:[1,0,0]
	v_max_f32_e32 v80, v80, v80
	v_pk_fma_f32 v[104:105], v[100:101], v[104:105], s[96:97] op_sel_hi:[1,1,0]
	v_max_f32_e32 v81, v81, v81
	v_pk_fma_f32 v[104:105], v[100:101], v[104:105], s[98:99] op_sel_hi:[1,1,0]
	v_and_b32_e32 v99, 0x7fffffff, v83
	v_pk_fma_f32 v[104:105], v[100:101], v[104:105], s[40:41] op_sel_hi:[1,1,0]
	v_and_b32_e32 v98, 0x7fffffff, v82
	v_pk_fma_f32 v[104:105], v[100:101], v[104:105], s[74:75] op_sel_hi:[1,1,0]
	v_max_f32_e32 v80, 0, v80
	v_pk_fma_f32 v[104:105], v[100:101], v[104:105], s[76:77] op_sel_hi:[1,1,0]
	v_max_f32_e32 v81, 0, v81
	v_pk_mul_f32 v[104:105], v[104:105], v[104:105]
	v_max_f32_e32 v82, v82, v82
	v_pk_mul_f32 v[104:105], v[104:105], v[104:105]
	v_max_f32_e32 v83, v83, v83
	v_pk_mul_f32 v[104:105], v[104:105], v[104:105]
	v_max_f32_e32 v82, 0, v82
	v_pk_mul_f32 v[104:105], v[104:105], v[104:105]
	v_max_f32_e32 v83, 0, v83
	v_rcp_f32_e32 v104, v104
	v_rcp_f32_e32 v105, v105
	v_pk_fma_f32 v[106:107], v[86:87], v[86:87], v[110:111]
	v_pk_fma_f32 v[100:101], v[100:101], v[104:105], v[80:81] neg_lo:[1,0,0] neg_hi:[1,0,0]
	v_pk_fma_f32 v[80:81], v[98:99], s[94:95], v[152:153] op_sel_hi:[1,0,0]
	v_pk_fma_f32 v[104:105], v[100:101], v[100:101], v[108:109]
	v_pk_fma_f32 v[80:81], v[98:99], v[80:81], s[96:97] op_sel_hi:[1,1,0]
	s_nop 0
	v_pk_fma_f32 v[80:81], v[98:99], v[80:81], s[98:99] op_sel_hi:[1,1,0]
	s_nop 0
	v_pk_fma_f32 v[80:81], v[98:99], v[80:81], s[40:41] op_sel_hi:[1,1,0]
	s_nop 0
	v_pk_fma_f32 v[80:81], v[98:99], v[80:81], s[74:75] op_sel_hi:[1,1,0]
	s_nop 0
	v_pk_fma_f32 v[80:81], v[98:99], v[80:81], s[76:77] op_sel_hi:[1,1,0]
	s_nop 0
	v_pk_mul_f32 v[80:81], v[80:81], v[80:81]
	s_nop 0
	v_pk_mul_f32 v[80:81], v[80:81], v[80:81]
	s_nop 0
	v_pk_mul_f32 v[80:81], v[80:81], v[80:81]
	s_nop 0
	v_pk_mul_f32 v[80:81], v[80:81], v[80:81]
	s_nop 0
	v_rcp_f32_e32 v80, v80
	v_rcp_f32_e32 v81, v81
	s_nop 0
	v_pk_fma_f32 v[98:99], v[98:99], v[80:81], v[82:83] neg_lo:[1,0,0] neg_hi:[1,0,0]
	v_cvt_pk_bf16_f32 v80, v84, v85
	v_mov_b32_e32 v85, s4
	v_or_b32_e32 v84, s1, v138
	v_lshlrev_b64 v[84:85], 10, v[84:85]
	v_cvt_pk_bf16_f32 v81, v86, v87
	v_cvt_pk_bf16_f32 v82, v100, v101
	v_cvt_pk_bf16_f32 v83, v98, v99
	v_lshl_add_u64 v[84:85], v[142:143], 0, v[84:85]
	global_store_dwordx4 v[84:85], v[80:83], off nt
	s_ashr_i32 s1, s0, 31
	s_lshl_b64 s[0:1], s[0:1], 5
	v_and_b32_e32 v83, 0x7fffffff, v77
	v_and_b32_e32 v82, 0x7fffffff, v76
	v_pk_fma_f32 v[86:87], v[82:83], s[94:95], v[152:153] op_sel_hi:[1,0,0]
	v_max_f32_e32 v76, v76, v76
	v_pk_fma_f32 v[86:87], v[82:83], v[86:87], s[96:97] op_sel_hi:[1,1,0]
	v_max_f32_e32 v77, v77, v77
	v_pk_fma_f32 v[86:87], v[82:83], v[86:87], s[98:99] op_sel_hi:[1,1,0]
	v_and_b32_e32 v81, 0x7fffffff, v79
	v_pk_fma_f32 v[86:87], v[82:83], v[86:87], s[40:41] op_sel_hi:[1,1,0]
	v_and_b32_e32 v80, 0x7fffffff, v78
	v_pk_fma_f32 v[86:87], v[82:83], v[86:87], s[74:75] op_sel_hi:[1,1,0]
	v_max_f32_e32 v76, 0, v76
	v_pk_fma_f32 v[86:87], v[82:83], v[86:87], s[76:77] op_sel_hi:[1,1,0]
	v_max_f32_e32 v77, 0, v77
	v_pk_mul_f32 v[86:87], v[86:87], v[86:87]
	v_max_f32_e32 v78, v78, v78
	v_pk_mul_f32 v[86:87], v[86:87], v[86:87]
	v_max_f32_e32 v79, v79, v79
	v_pk_mul_f32 v[86:87], v[86:87], v[86:87]
	v_max_f32_e32 v78, 0, v78
	v_pk_mul_f32 v[86:87], v[86:87], v[86:87]
	v_max_f32_e32 v79, 0, v79
	v_rcp_f32_e32 v86, v86
	v_rcp_f32_e32 v87, v87
	s_add_u32 s4, s0, s41
	s_addc_u32 s5, s1, 0
	s_add_u32 s11, s4, vcc_lo
	v_pk_fma_f32 v[76:77], v[82:83], v[86:87], v[76:77] neg_lo:[1,0,0] neg_hi:[1,0,0]
	v_pk_fma_f32 v[82:83], v[80:81], s[94:95], v[152:153] op_sel_hi:[1,0,0]
	v_pk_fma_f32 v[108:109], v[98:99], v[98:99], v[112:113]
	v_pk_fma_f32 v[82:83], v[80:81], v[82:83], s[96:97] op_sel_hi:[1,1,0]
	s_addc_u32 s12, s5, vcc_hi
	v_pk_fma_f32 v[82:83], v[80:81], v[82:83], s[98:99] op_sel_hi:[1,1,0]
	s_add_u32 s4, s82, s4
	v_pk_fma_f32 v[82:83], v[80:81], v[82:83], s[40:41] op_sel_hi:[1,1,0]
	s_addc_u32 s5, s83, s5
	v_pk_fma_f32 v[82:83], v[80:81], v[82:83], s[74:75] op_sel_hi:[1,1,0]
	s_add_u32 s0, s0, s6
	v_pk_fma_f32 v[82:83], v[80:81], v[82:83], s[76:77] op_sel_hi:[1,1,0]
	s_addc_u32 s1, s1, 0
	v_pk_mul_f32 v[82:83], v[82:83], v[82:83]
	s_nop 0
	v_pk_mul_f32 v[82:83], v[82:83], v[82:83]
	s_nop 0
	v_pk_mul_f32 v[82:83], v[82:83], v[82:83]
	s_nop 0
	v_pk_mul_f32 v[82:83], v[82:83], v[82:83]
	s_nop 0
	v_rcp_f32_e32 v82, v82
	v_rcp_f32_e32 v83, v83
	s_nop 0
	v_pk_fma_f32 v[78:79], v[80:81], v[82:83], v[78:79] neg_lo:[1,0,0] neg_hi:[1,0,0]
	v_and_b32_e32 v83, 0x7fffffff, v73
	v_and_b32_e32 v82, 0x7fffffff, v72
	v_pk_fma_f32 v[86:87], v[82:83], s[94:95], v[152:153] op_sel_hi:[1,0,0]
	v_max_f32_e32 v72, v72, v72
	v_pk_fma_f32 v[86:87], v[82:83], v[86:87], s[96:97] op_sel_hi:[1,1,0]
	v_max_f32_e32 v73, v73, v73
	v_pk_fma_f32 v[86:87], v[82:83], v[86:87], s[98:99] op_sel_hi:[1,1,0]
	v_and_b32_e32 v81, 0x7fffffff, v75
	v_pk_fma_f32 v[86:87], v[82:83], v[86:87], s[40:41] op_sel_hi:[1,1,0]
	v_and_b32_e32 v80, 0x7fffffff, v74
	v_pk_fma_f32 v[86:87], v[82:83], v[86:87], s[74:75] op_sel_hi:[1,1,0]
	v_max_f32_e32 v72, 0, v72
	v_pk_fma_f32 v[86:87], v[82:83], v[86:87], s[76:77] op_sel_hi:[1,1,0]
	v_max_f32_e32 v73, 0, v73
	v_pk_mul_f32 v[86:87], v[86:87], v[86:87]
	v_max_f32_e32 v74, v74, v74
	v_pk_mul_f32 v[86:87], v[86:87], v[86:87]
	v_max_f32_e32 v75, v75, v75
	v_pk_mul_f32 v[86:87], v[86:87], v[86:87]
	v_max_f32_e32 v74, 0, v74
	v_pk_mul_f32 v[86:87], v[86:87], v[86:87]
	v_max_f32_e32 v75, 0, v75
	v_rcp_f32_e32 v86, v86
	v_rcp_f32_e32 v87, v87
	s_nop 0
	v_pk_fma_f32 v[82:83], v[82:83], v[86:87], v[72:73] neg_lo:[1,0,0] neg_hi:[1,0,0]
	v_pk_fma_f32 v[72:73], v[80:81], s[94:95], v[152:153] op_sel_hi:[1,0,0]
	v_pk_fma_f32 v[86:87], v[76:77], v[76:77], v[88:89]
	v_pk_fma_f32 v[72:73], v[80:81], v[72:73], s[96:97] op_sel_hi:[1,1,0]
	v_pk_fma_f32 v[88:89], v[82:83], v[82:83], v[90:91]
	v_pk_fma_f32 v[72:73], v[80:81], v[72:73], s[98:99] op_sel_hi:[1,1,0]
	v_pk_fma_f32 v[90:91], v[78:79], v[78:79], v[92:93]
	v_pk_fma_f32 v[72:73], v[80:81], v[72:73], s[40:41] op_sel_hi:[1,1,0]
	s_nop 0
	v_pk_fma_f32 v[72:73], v[80:81], v[72:73], s[74:75] op_sel_hi:[1,1,0]
	s_nop 0
	v_pk_fma_f32 v[72:73], v[80:81], v[72:73], s[76:77] op_sel_hi:[1,1,0]
	s_nop 0
	v_pk_mul_f32 v[72:73], v[72:73], v[72:73]
	s_nop 0
	v_pk_mul_f32 v[72:73], v[72:73], v[72:73]
	s_nop 0
	v_pk_mul_f32 v[72:73], v[72:73], v[72:73]
	s_nop 0
	v_pk_mul_f32 v[72:73], v[72:73], v[72:73]
	s_nop 0
	v_rcp_f32_e32 v72, v72
	v_rcp_f32_e32 v73, v73
	s_nop 0
	v_pk_fma_f32 v[80:81], v[80:81], v[72:73], v[74:75] neg_lo:[1,0,0] neg_hi:[1,0,0]
	v_cvt_pk_bf16_f32 v72, v76, v77
	v_cvt_pk_bf16_f32 v73, v78, v79
	v_cvt_pk_bf16_f32 v74, v82, v83
	s_nop 0
	v_cvt_pk_bf16_f32 v75, v80, v81
	global_store_dwordx4 v[102:103], v[72:75], off offset:128 nt
	v_pk_fma_f32 v[92:93], v[80:81], v[80:81], v[94:95]
	s_nop 0
	v_and_b32_e32 v75, 0x7fffffff, v69
	v_and_b32_e32 v74, 0x7fffffff, v68
	v_pk_fma_f32 v[76:77], v[74:75], s[94:95], v[152:153] op_sel_hi:[1,0,0]
	v_max_f32_e32 v68, v68, v68
	v_pk_fma_f32 v[76:77], v[74:75], v[76:77], s[96:97] op_sel_hi:[1,1,0]
	v_max_f32_e32 v69, v69, v69
	v_pk_fma_f32 v[76:77], v[74:75], v[76:77], s[98:99] op_sel_hi:[1,1,0]
	v_and_b32_e32 v73, 0x7fffffff, v71
	v_pk_fma_f32 v[76:77], v[74:75], v[76:77], s[40:41] op_sel_hi:[1,1,0]
	v_and_b32_e32 v72, 0x7fffffff, v70
	v_pk_fma_f32 v[76:77], v[74:75], v[76:77], s[74:75] op_sel_hi:[1,1,0]
	v_max_f32_e32 v68, 0, v68
	v_pk_fma_f32 v[76:77], v[74:75], v[76:77], s[76:77] op_sel_hi:[1,1,0]
	v_max_f32_e32 v69, 0, v69
	v_pk_mul_f32 v[76:77], v[76:77], v[76:77]
	v_max_f32_e32 v70, v70, v70
	v_pk_mul_f32 v[76:77], v[76:77], v[76:77]
	v_max_f32_e32 v71, v71, v71
	v_pk_mul_f32 v[76:77], v[76:77], v[76:77]
	v_max_f32_e32 v70, 0, v70
	v_pk_mul_f32 v[76:77], v[76:77], v[76:77]
	v_max_f32_e32 v71, 0, v71
	v_rcp_f32_e32 v76, v76
	v_rcp_f32_e32 v77, v77
	s_nop 0
	v_pk_fma_f32 v[74:75], v[74:75], v[76:77], v[68:69] neg_lo:[1,0,0] neg_hi:[1,0,0]
	v_pk_fma_f32 v[68:69], v[72:73], s[94:95], v[152:153] op_sel_hi:[1,0,0]
	s_nop 0
	v_pk_fma_f32 v[68:69], v[72:73], v[68:69], s[96:97] op_sel_hi:[1,1,0]
	s_nop 0
	v_pk_fma_f32 v[68:69], v[72:73], v[68:69], s[98:99] op_sel_hi:[1,1,0]
	s_nop 0
	v_pk_fma_f32 v[68:69], v[72:73], v[68:69], s[40:41] op_sel_hi:[1,1,0]
	s_nop 0
	v_pk_fma_f32 v[68:69], v[72:73], v[68:69], s[74:75] op_sel_hi:[1,1,0]
	s_nop 0
	v_pk_fma_f32 v[68:69], v[72:73], v[68:69], s[76:77] op_sel_hi:[1,1,0]
	s_nop 0
	v_pk_mul_f32 v[68:69], v[68:69], v[68:69]
	s_nop 0
	v_pk_mul_f32 v[68:69], v[68:69], v[68:69]
	s_nop 0
	v_pk_mul_f32 v[68:69], v[68:69], v[68:69]
	s_nop 0
	v_pk_mul_f32 v[68:69], v[68:69], v[68:69]
	s_nop 0
	v_rcp_f32_e32 v68, v68
	v_rcp_f32_e32 v69, v69
	s_nop 0
	v_pk_fma_f32 v[76:77], v[72:73], v[68:69], v[70:71] neg_lo:[1,0,0] neg_hi:[1,0,0]
	v_and_b32_e32 v71, 0x7fffffff, v65
	v_and_b32_e32 v70, 0x7fffffff, v64
	v_pk_fma_f32 v[72:73], v[70:71], s[94:95], v[152:153] op_sel_hi:[1,0,0]
	v_max_f32_e32 v64, v64, v64
	v_pk_fma_f32 v[72:73], v[70:71], v[72:73], s[96:97] op_sel_hi:[1,1,0]
	v_max_f32_e32 v65, v65, v65
	v_pk_fma_f32 v[72:73], v[70:71], v[72:73], s[98:99] op_sel_hi:[1,1,0]
	v_and_b32_e32 v69, 0x7fffffff, v67
	v_pk_fma_f32 v[72:73], v[70:71], v[72:73], s[40:41] op_sel_hi:[1,1,0]
	v_and_b32_e32 v68, 0x7fffffff, v66
	v_pk_fma_f32 v[72:73], v[70:71], v[72:73], s[74:75] op_sel_hi:[1,1,0]
	v_max_f32_e32 v64, 0, v64
	v_pk_fma_f32 v[72:73], v[70:71], v[72:73], s[76:77] op_sel_hi:[1,1,0]
	v_max_f32_e32 v65, 0, v65
	v_pk_mul_f32 v[72:73], v[72:73], v[72:73]
	v_max_f32_e32 v66, v66, v66
	v_pk_mul_f32 v[72:73], v[72:73], v[72:73]
	v_max_f32_e32 v67, v67, v67
	v_pk_mul_f32 v[72:73], v[72:73], v[72:73]
	v_max_f32_e32 v66, 0, v66
	v_pk_mul_f32 v[72:73], v[72:73], v[72:73]
	v_max_f32_e32 v67, 0, v67
	v_rcp_f32_e32 v72, v72
	v_rcp_f32_e32 v73, v73
	s_nop 0
	v_pk_fma_f32 v[78:79], v[70:71], v[72:73], v[64:65] neg_lo:[1,0,0] neg_hi:[1,0,0]
	v_pk_fma_f32 v[64:65], v[68:69], s[94:95], v[152:153] op_sel_hi:[1,0,0]
	v_cvt_pk_bf16_f32 v72, v74, v75
	v_cvt_pk_bf16_f32 v73, v76, v77
	s_nop 0
	v_pk_fma_f32 v[64:65], v[68:69], v[64:65], s[96:97] op_sel_hi:[1,1,0]
	s_nop 0
	v_pk_fma_f32 v[64:65], v[68:69], v[64:65], s[98:99] op_sel_hi:[1,1,0]
	s_nop 0
	v_pk_fma_f32 v[64:65], v[68:69], v[64:65], s[40:41] op_sel_hi:[1,1,0]
	s_nop 0
	v_pk_fma_f32 v[64:65], v[68:69], v[64:65], s[74:75] op_sel_hi:[1,1,0]
	s_nop 0
	v_pk_fma_f32 v[64:65], v[68:69], v[64:65], s[76:77] op_sel_hi:[1,1,0]
	s_nop 0
	v_pk_mul_f32 v[64:65], v[64:65], v[64:65]
	s_nop 0
	v_pk_mul_f32 v[64:65], v[64:65], v[64:65]
	s_nop 0
	v_pk_mul_f32 v[64:65], v[64:65], v[64:65]
	s_nop 0
	v_pk_mul_f32 v[64:65], v[64:65], v[64:65]
	s_nop 0
	v_rcp_f32_e32 v64, v64
	v_rcp_f32_e32 v65, v65
	s_nop 0
	v_pk_fma_f32 v[80:81], v[68:69], v[64:65], v[66:67] neg_lo:[1,0,0] neg_hi:[1,0,0]
	v_pk_fma_f32 v[64:65], v[74:75], v[74:75], v[96:97]
	v_cvt_pk_bf16_f32 v74, v78, v79
	v_cvt_pk_bf16_f32 v75, v80, v81
	global_store_dwordx4 v[84:85], v[72:75], off offset:128 nt
	v_pk_fma_f32 v[68:69], v[76:77], v[76:77], v[106:107]
	v_pk_fma_f32 v[66:67], v[78:79], v[78:79], v[104:105]
	v_and_b32_e32 v75, 0x7fffffff, v61
	v_and_b32_e32 v74, 0x7fffffff, v60
	v_pk_fma_f32 v[76:77], v[74:75], s[94:95], v[152:153] op_sel_hi:[1,0,0]
	v_max_f32_e32 v60, v60, v60
	v_pk_fma_f32 v[76:77], v[74:75], v[76:77], s[96:97] op_sel_hi:[1,1,0]
	v_max_f32_e32 v61, v61, v61
	v_pk_fma_f32 v[76:77], v[74:75], v[76:77], s[98:99] op_sel_hi:[1,1,0]
	v_and_b32_e32 v73, 0x7fffffff, v63
	v_pk_fma_f32 v[76:77], v[74:75], v[76:77], s[40:41] op_sel_hi:[1,1,0]
	v_and_b32_e32 v72, 0x7fffffff, v62
	v_pk_fma_f32 v[76:77], v[74:75], v[76:77], s[74:75] op_sel_hi:[1,1,0]
	v_max_f32_e32 v60, 0, v60
	v_pk_fma_f32 v[76:77], v[74:75], v[76:77], s[76:77] op_sel_hi:[1,1,0]
	v_max_f32_e32 v61, 0, v61
	v_pk_mul_f32 v[76:77], v[76:77], v[76:77]
	v_max_f32_e32 v62, v62, v62
	v_pk_mul_f32 v[76:77], v[76:77], v[76:77]
	v_max_f32_e32 v63, v63, v63
	v_pk_mul_f32 v[76:77], v[76:77], v[76:77]
	v_max_f32_e32 v62, 0, v62
	v_pk_mul_f32 v[76:77], v[76:77], v[76:77]
	v_max_f32_e32 v63, 0, v63
	v_rcp_f32_e32 v76, v76
	v_rcp_f32_e32 v77, v77
	v_pk_fma_f32 v[70:71], v[80:81], v[80:81], v[108:109]
	v_pk_fma_f32 v[74:75], v[74:75], v[76:77], v[60:61] neg_lo:[1,0,0] neg_hi:[1,0,0]
	v_pk_fma_f32 v[60:61], v[72:73], s[94:95], v[152:153] op_sel_hi:[1,0,0]
	s_nop 0
	v_pk_fma_f32 v[60:61], v[72:73], v[60:61], s[96:97] op_sel_hi:[1,1,0]
	s_nop 0
	v_pk_fma_f32 v[60:61], v[72:73], v[60:61], s[98:99] op_sel_hi:[1,1,0]
	s_nop 0
	v_pk_fma_f32 v[60:61], v[72:73], v[60:61], s[40:41] op_sel_hi:[1,1,0]
	s_nop 0
	v_pk_fma_f32 v[60:61], v[72:73], v[60:61], s[74:75] op_sel_hi:[1,1,0]
	s_nop 0
	v_pk_fma_f32 v[60:61], v[72:73], v[60:61], s[76:77] op_sel_hi:[1,1,0]
	s_nop 0
	v_pk_mul_f32 v[60:61], v[60:61], v[60:61]
	s_nop 0
	v_pk_mul_f32 v[60:61], v[60:61], v[60:61]
	s_nop 0
	v_pk_mul_f32 v[60:61], v[60:61], v[60:61]
	s_nop 0
	v_pk_mul_f32 v[60:61], v[60:61], v[60:61]
	s_nop 0
	v_rcp_f32_e32 v60, v60
	v_rcp_f32_e32 v61, v61
	s_nop 0
	v_pk_fma_f32 v[76:77], v[72:73], v[60:61], v[62:63] neg_lo:[1,0,0] neg_hi:[1,0,0]
	v_and_b32_e32 v63, 0x7fffffff, v57
	v_and_b32_e32 v62, 0x7fffffff, v56
	v_pk_fma_f32 v[72:73], v[62:63], s[94:95], v[152:153] op_sel_hi:[1,0,0]
	v_max_f32_e32 v56, v56, v56
	v_pk_fma_f32 v[72:73], v[62:63], v[72:73], s[96:97] op_sel_hi:[1,1,0]
	v_max_f32_e32 v57, v57, v57
	v_pk_fma_f32 v[72:73], v[62:63], v[72:73], s[98:99] op_sel_hi:[1,1,0]
	v_and_b32_e32 v61, 0x7fffffff, v59
	v_pk_fma_f32 v[72:73], v[62:63], v[72:73], s[40:41] op_sel_hi:[1,1,0]
	v_and_b32_e32 v60, 0x7fffffff, v58
	v_pk_fma_f32 v[72:73], v[62:63], v[72:73], s[74:75] op_sel_hi:[1,1,0]
	v_max_f32_e32 v56, 0, v56
	v_pk_fma_f32 v[72:73], v[62:63], v[72:73], s[76:77] op_sel_hi:[1,1,0]
	v_max_f32_e32 v57, 0, v57
	v_pk_mul_f32 v[72:73], v[72:73], v[72:73]
	v_max_f32_e32 v58, v58, v58
	v_pk_mul_f32 v[72:73], v[72:73], v[72:73]
	v_max_f32_e32 v59, v59, v59
	v_pk_mul_f32 v[72:73], v[72:73], v[72:73]
	v_max_f32_e32 v58, 0, v58
	v_pk_mul_f32 v[72:73], v[72:73], v[72:73]
	v_max_f32_e32 v59, 0, v59
	v_rcp_f32_e32 v72, v72
	v_rcp_f32_e32 v73, v73
	s_nop 0
	v_pk_fma_f32 v[78:79], v[62:63], v[72:73], v[56:57] neg_lo:[1,0,0] neg_hi:[1,0,0]
	v_pk_fma_f32 v[56:57], v[60:61], s[94:95], v[152:153] op_sel_hi:[1,0,0]
	v_cvt_pk_bf16_f32 v72, v74, v75
	v_cvt_pk_bf16_f32 v73, v76, v77
	s_nop 0
	v_pk_fma_f32 v[56:57], v[60:61], v[56:57], s[96:97] op_sel_hi:[1,1,0]
	s_nop 0
	v_pk_fma_f32 v[56:57], v[60:61], v[56:57], s[98:99] op_sel_hi:[1,1,0]
	s_nop 0
	v_pk_fma_f32 v[56:57], v[60:61], v[56:57], s[40:41] op_sel_hi:[1,1,0]
	s_nop 0
	v_pk_fma_f32 v[56:57], v[60:61], v[56:57], s[74:75] op_sel_hi:[1,1,0]
	s_nop 0
	v_pk_fma_f32 v[56:57], v[60:61], v[56:57], s[76:77] op_sel_hi:[1,1,0]
	s_nop 0
	v_pk_mul_f32 v[56:57], v[56:57], v[56:57]
	s_nop 0
	v_pk_mul_f32 v[56:57], v[56:57], v[56:57]
	s_nop 0
	v_pk_mul_f32 v[56:57], v[56:57], v[56:57]
	s_nop 0
	v_pk_mul_f32 v[56:57], v[56:57], v[56:57]
	s_nop 0
	v_rcp_f32_e32 v56, v56
	v_rcp_f32_e32 v57, v57
	s_nop 0
	v_pk_fma_f32 v[80:81], v[60:61], v[56:57], v[58:59] neg_lo:[1,0,0] neg_hi:[1,0,0]
	v_pk_fma_f32 v[60:61], v[76:77], v[76:77], v[90:91]
	v_mov_b32_e32 v77, s12
	v_or_b32_e32 v76, s11, v138
	v_lshlrev_b64 v[76:77], 10, v[76:77]
	v_pk_fma_f32 v[56:57], v[74:75], v[74:75], v[86:87]
	v_cvt_pk_bf16_f32 v74, v78, v79
	v_cvt_pk_bf16_f32 v75, v80, v81
	v_lshl_add_u64 v[76:77], v[142:143], 0, v[76:77]
	global_store_dwordx4 v[76:77], v[72:75], off nt
	v_pk_fma_f32 v[58:59], v[78:79], v[78:79], v[88:89]
	v_pk_fma_f32 v[62:63], v[80:81], v[80:81], v[92:93]
	v_and_b32_e32 v75, 0x7fffffff, v53
	v_and_b32_e32 v74, 0x7fffffff, v52
	v_pk_fma_f32 v[78:79], v[74:75], s[94:95], v[152:153] op_sel_hi:[1,0,0]
	v_max_f32_e32 v52, v52, v52
	v_pk_fma_f32 v[78:79], v[74:75], v[78:79], s[96:97] op_sel_hi:[1,1,0]
	v_max_f32_e32 v53, v53, v53
	v_pk_fma_f32 v[78:79], v[74:75], v[78:79], s[98:99] op_sel_hi:[1,1,0]
	v_and_b32_e32 v73, 0x7fffffff, v55
	v_pk_fma_f32 v[78:79], v[74:75], v[78:79], s[40:41] op_sel_hi:[1,1,0]
	v_and_b32_e32 v72, 0x7fffffff, v54
	v_pk_fma_f32 v[78:79], v[74:75], v[78:79], s[74:75] op_sel_hi:[1,1,0]
	v_max_f32_e32 v52, 0, v52
	v_pk_fma_f32 v[78:79], v[74:75], v[78:79], s[76:77] op_sel_hi:[1,1,0]
	v_max_f32_e32 v53, 0, v53
	v_pk_mul_f32 v[78:79], v[78:79], v[78:79]
	v_max_f32_e32 v54, v54, v54
	v_pk_mul_f32 v[78:79], v[78:79], v[78:79]
	v_max_f32_e32 v55, v55, v55
	v_pk_mul_f32 v[78:79], v[78:79], v[78:79]
	v_max_f32_e32 v54, 0, v54
	v_pk_mul_f32 v[78:79], v[78:79], v[78:79]
	v_max_f32_e32 v55, 0, v55
	v_rcp_f32_e32 v78, v78
	v_rcp_f32_e32 v79, v79
	s_nop 0
	v_pk_fma_f32 v[52:53], v[74:75], v[78:79], v[52:53] neg_lo:[1,0,0] neg_hi:[1,0,0]
	v_pk_fma_f32 v[74:75], v[72:73], s[94:95], v[152:153] op_sel_hi:[1,0,0]
	v_pk_fma_f32 v[64:65], v[52:53], v[52:53], v[64:65]
	v_pk_fma_f32 v[74:75], v[72:73], v[74:75], s[96:97] op_sel_hi:[1,1,0]
	s_nop 0
	v_pk_fma_f32 v[74:75], v[72:73], v[74:75], s[98:99] op_sel_hi:[1,1,0]
	s_nop 0
	v_pk_fma_f32 v[74:75], v[72:73], v[74:75], s[40:41] op_sel_hi:[1,1,0]
	s_nop 0
	v_pk_fma_f32 v[74:75], v[72:73], v[74:75], s[74:75] op_sel_hi:[1,1,0]
	s_nop 0
	v_pk_fma_f32 v[74:75], v[72:73], v[74:75], s[76:77] op_sel_hi:[1,1,0]
	s_nop 0
	v_pk_mul_f32 v[74:75], v[74:75], v[74:75]
	s_nop 0
	v_pk_mul_f32 v[74:75], v[74:75], v[74:75]
	s_nop 0
	v_pk_mul_f32 v[74:75], v[74:75], v[74:75]
	s_nop 0
	v_pk_mul_f32 v[74:75], v[74:75], v[74:75]
	s_nop 0
	v_rcp_f32_e32 v74, v74
	v_rcp_f32_e32 v75, v75
	s_nop 0
	v_pk_fma_f32 v[54:55], v[72:73], v[74:75], v[54:55] neg_lo:[1,0,0] neg_hi:[1,0,0]
	v_and_b32_e32 v75, 0x7fffffff, v49
	v_and_b32_e32 v74, 0x7fffffff, v48
	v_pk_fma_f32 v[78:79], v[74:75], s[94:95], v[152:153] op_sel_hi:[1,0,0]
	v_max_f32_e32 v48, v48, v48
	v_pk_fma_f32 v[78:79], v[74:75], v[78:79], s[96:97] op_sel_hi:[1,1,0]
	v_max_f32_e32 v49, v49, v49
	v_pk_fma_f32 v[78:79], v[74:75], v[78:79], s[98:99] op_sel_hi:[1,1,0]
	v_and_b32_e32 v73, 0x7fffffff, v51
	v_pk_fma_f32 v[78:79], v[74:75], v[78:79], s[40:41] op_sel_hi:[1,1,0]
	v_and_b32_e32 v72, 0x7fffffff, v50
	v_pk_fma_f32 v[78:79], v[74:75], v[78:79], s[74:75] op_sel_hi:[1,1,0]
	v_max_f32_e32 v48, 0, v48
	v_pk_fma_f32 v[78:79], v[74:75], v[78:79], s[76:77] op_sel_hi:[1,1,0]
	v_max_f32_e32 v49, 0, v49
	v_pk_mul_f32 v[78:79], v[78:79], v[78:79]
	v_max_f32_e32 v50, v50, v50
	v_pk_mul_f32 v[78:79], v[78:79], v[78:79]
	v_max_f32_e32 v51, v51, v51
	v_pk_mul_f32 v[78:79], v[78:79], v[78:79]
	v_max_f32_e32 v50, 0, v50
	v_pk_mul_f32 v[78:79], v[78:79], v[78:79]
	v_max_f32_e32 v51, 0, v51
	v_rcp_f32_e32 v78, v78
	v_rcp_f32_e32 v79, v79
	v_pk_fma_f32 v[68:69], v[54:55], v[54:55], v[68:69]
	v_pk_fma_f32 v[74:75], v[74:75], v[78:79], v[48:49] neg_lo:[1,0,0] neg_hi:[1,0,0]
	v_pk_fma_f32 v[48:49], v[72:73], s[94:95], v[152:153] op_sel_hi:[1,0,0]
	v_pk_fma_f32 v[66:67], v[74:75], v[74:75], v[66:67]
	v_pk_fma_f32 v[48:49], v[72:73], v[48:49], s[96:97] op_sel_hi:[1,1,0]
	s_nop 0
	v_pk_fma_f32 v[48:49], v[72:73], v[48:49], s[98:99] op_sel_hi:[1,1,0]
	s_nop 0
	v_pk_fma_f32 v[48:49], v[72:73], v[48:49], s[40:41] op_sel_hi:[1,1,0]
	s_nop 0
	v_pk_fma_f32 v[48:49], v[72:73], v[48:49], s[74:75] op_sel_hi:[1,1,0]
	s_nop 0
	v_pk_fma_f32 v[48:49], v[72:73], v[48:49], s[76:77] op_sel_hi:[1,1,0]
	s_nop 0
	v_pk_mul_f32 v[48:49], v[48:49], v[48:49]
	s_nop 0
	v_pk_mul_f32 v[48:49], v[48:49], v[48:49]
	s_nop 0
	v_pk_mul_f32 v[48:49], v[48:49], v[48:49]
	s_nop 0
	v_pk_mul_f32 v[48:49], v[48:49], v[48:49]
	s_nop 0
	v_rcp_f32_e32 v48, v48
	v_rcp_f32_e32 v49, v49
	s_nop 0
	v_pk_fma_f32 v[72:73], v[72:73], v[48:49], v[50:51] neg_lo:[1,0,0] neg_hi:[1,0,0]
	v_cvt_pk_bf16_f32 v48, v52, v53
	v_mov_b32_e32 v53, s5
	v_or_b32_e32 v52, s4, v138
	v_lshlrev_b64 v[52:53], 10, v[52:53]
	v_cvt_pk_bf16_f32 v49, v54, v55
	v_cvt_pk_bf16_f32 v50, v74, v75
	v_cvt_pk_bf16_f32 v51, v72, v73
	v_lshl_add_u64 v[52:53], v[142:143], 0, v[52:53]
	global_store_dwordx4 v[52:53], v[48:51], off nt
	s_add_u32 s4, s0, vcc_lo
	v_pk_fma_f32 v[70:71], v[72:73], v[72:73], v[70:71]
	v_and_b32_e32 v51, 0x7fffffff, v45
	v_and_b32_e32 v50, 0x7fffffff, v44
	v_pk_fma_f32 v[54:55], v[50:51], s[94:95], v[152:153] op_sel_hi:[1,0,0]
	v_max_f32_e32 v44, v44, v44
	v_pk_fma_f32 v[54:55], v[50:51], v[54:55], s[96:97] op_sel_hi:[1,1,0]
	v_max_f32_e32 v45, v45, v45
	v_pk_fma_f32 v[54:55], v[50:51], v[54:55], s[98:99] op_sel_hi:[1,1,0]
	v_and_b32_e32 v49, 0x7fffffff, v47
	v_pk_fma_f32 v[54:55], v[50:51], v[54:55], s[40:41] op_sel_hi:[1,1,0]
	v_and_b32_e32 v48, 0x7fffffff, v46
	v_pk_fma_f32 v[54:55], v[50:51], v[54:55], s[74:75] op_sel_hi:[1,1,0]
	v_max_f32_e32 v44, 0, v44
	v_pk_fma_f32 v[54:55], v[50:51], v[54:55], s[76:77] op_sel_hi:[1,1,0]
	v_max_f32_e32 v45, 0, v45
	v_pk_mul_f32 v[54:55], v[54:55], v[54:55]
	v_max_f32_e32 v46, v46, v46
	v_pk_mul_f32 v[54:55], v[54:55], v[54:55]
	v_max_f32_e32 v47, v47, v47
	v_pk_mul_f32 v[54:55], v[54:55], v[54:55]
	v_max_f32_e32 v46, 0, v46
	v_pk_mul_f32 v[54:55], v[54:55], v[54:55]
	v_max_f32_e32 v47, 0, v47
	v_rcp_f32_e32 v54, v54
	v_rcp_f32_e32 v55, v55
	s_addc_u32 s5, s1, vcc_hi
	s_add_u32 s0, s82, s0
	s_addc_u32 s1, s83, s1
	v_pk_fma_f32 v[44:45], v[50:51], v[54:55], v[44:45] neg_lo:[1,0,0] neg_hi:[1,0,0]
	v_pk_fma_f32 v[50:51], v[48:49], s[94:95], v[152:153] op_sel_hi:[1,0,0]
	s_andn2_b64 vcc, exec, s[88:89]
	v_pk_fma_f32 v[50:51], v[48:49], v[50:51], s[96:97] op_sel_hi:[1,1,0]
	s_nop 0
	v_pk_fma_f32 v[50:51], v[48:49], v[50:51], s[98:99] op_sel_hi:[1,1,0]
	s_nop 0
	v_pk_fma_f32 v[50:51], v[48:49], v[50:51], s[40:41] op_sel_hi:[1,1,0]
	s_nop 0
	v_pk_fma_f32 v[50:51], v[48:49], v[50:51], s[74:75] op_sel_hi:[1,1,0]
	s_nop 0
	v_pk_fma_f32 v[50:51], v[48:49], v[50:51], s[76:77] op_sel_hi:[1,1,0]
	s_nop 0
	v_pk_mul_f32 v[50:51], v[50:51], v[50:51]
	s_nop 0
	v_pk_mul_f32 v[50:51], v[50:51], v[50:51]
	s_nop 0
	v_pk_mul_f32 v[50:51], v[50:51], v[50:51]
	s_nop 0
	v_pk_mul_f32 v[50:51], v[50:51], v[50:51]
	s_nop 0
	v_rcp_f32_e32 v50, v50
	v_rcp_f32_e32 v51, v51
	s_nop 0
	v_pk_fma_f32 v[46:47], v[48:49], v[50:51], v[46:47] neg_lo:[1,0,0] neg_hi:[1,0,0]
	v_and_b32_e32 v51, 0x7fffffff, v41
	v_and_b32_e32 v50, 0x7fffffff, v40
	v_pk_fma_f32 v[54:55], v[50:51], s[94:95], v[152:153] op_sel_hi:[1,0,0]
	v_max_f32_e32 v40, v40, v40
	v_pk_fma_f32 v[54:55], v[50:51], v[54:55], s[96:97] op_sel_hi:[1,1,0]
	v_max_f32_e32 v41, v41, v41
	v_pk_fma_f32 v[54:55], v[50:51], v[54:55], s[98:99] op_sel_hi:[1,1,0]
	v_and_b32_e32 v49, 0x7fffffff, v43
	v_pk_fma_f32 v[54:55], v[50:51], v[54:55], s[40:41] op_sel_hi:[1,1,0]
	v_and_b32_e32 v48, 0x7fffffff, v42
	v_pk_fma_f32 v[54:55], v[50:51], v[54:55], s[74:75] op_sel_hi:[1,1,0]
	v_max_f32_e32 v40, 0, v40
	v_pk_fma_f32 v[54:55], v[50:51], v[54:55], s[76:77] op_sel_hi:[1,1,0]
	v_max_f32_e32 v41, 0, v41
	v_pk_mul_f32 v[54:55], v[54:55], v[54:55]
	v_max_f32_e32 v42, v42, v42
	v_pk_mul_f32 v[54:55], v[54:55], v[54:55]
	v_max_f32_e32 v43, v43, v43
	v_pk_mul_f32 v[54:55], v[54:55], v[54:55]
	v_max_f32_e32 v42, 0, v42
	v_pk_mul_f32 v[54:55], v[54:55], v[54:55]
	v_max_f32_e32 v43, 0, v43
	v_rcp_f32_e32 v54, v54
	v_rcp_f32_e32 v55, v55
	s_nop 0
	v_pk_fma_f32 v[50:51], v[50:51], v[54:55], v[40:41] neg_lo:[1,0,0] neg_hi:[1,0,0]
	v_pk_fma_f32 v[40:41], v[48:49], s[94:95], v[152:153] op_sel_hi:[1,0,0]
	v_pk_fma_f32 v[54:55], v[44:45], v[44:45], v[56:57]
	v_pk_fma_f32 v[40:41], v[48:49], v[40:41], s[96:97] op_sel_hi:[1,1,0]
	v_pk_fma_f32 v[56:57], v[50:51], v[50:51], v[58:59]
	v_pk_fma_f32 v[40:41], v[48:49], v[40:41], s[98:99] op_sel_hi:[1,1,0]
	v_pk_fma_f32 v[58:59], v[46:47], v[46:47], v[60:61]
	v_pk_fma_f32 v[40:41], v[48:49], v[40:41], s[40:41] op_sel_hi:[1,1,0]
	s_nop 0
	v_pk_fma_f32 v[40:41], v[48:49], v[40:41], s[74:75] op_sel_hi:[1,1,0]
	s_nop 0
	v_pk_fma_f32 v[40:41], v[48:49], v[40:41], s[76:77] op_sel_hi:[1,1,0]
	s_nop 0
	v_pk_mul_f32 v[40:41], v[40:41], v[40:41]
	s_nop 0
	v_pk_mul_f32 v[40:41], v[40:41], v[40:41]
	s_nop 0
	v_pk_mul_f32 v[40:41], v[40:41], v[40:41]
	s_nop 0
	v_pk_mul_f32 v[40:41], v[40:41], v[40:41]
	s_nop 0
	v_rcp_f32_e32 v40, v40
	v_rcp_f32_e32 v41, v41
	s_nop 0
	v_pk_fma_f32 v[48:49], v[48:49], v[40:41], v[42:43] neg_lo:[1,0,0] neg_hi:[1,0,0]
	v_cvt_pk_bf16_f32 v40, v44, v45
	v_cvt_pk_bf16_f32 v41, v46, v47
	v_cvt_pk_bf16_f32 v42, v50, v51
	s_nop 0
	v_cvt_pk_bf16_f32 v43, v48, v49
	global_store_dwordx4 v[76:77], v[40:43], off offset:128 nt
	v_pk_fma_f32 v[60:61], v[48:49], v[48:49], v[62:63]
	s_nop 0
	v_and_b32_e32 v43, 0x7fffffff, v37
	v_and_b32_e32 v42, 0x7fffffff, v36
	v_pk_fma_f32 v[44:45], v[42:43], s[94:95], v[152:153] op_sel_hi:[1,0,0]
	v_max_f32_e32 v36, v36, v36
	v_pk_fma_f32 v[44:45], v[42:43], v[44:45], s[96:97] op_sel_hi:[1,1,0]
	v_max_f32_e32 v37, v37, v37
	v_pk_fma_f32 v[44:45], v[42:43], v[44:45], s[98:99] op_sel_hi:[1,1,0]
	v_and_b32_e32 v41, 0x7fffffff, v39
	v_pk_fma_f32 v[44:45], v[42:43], v[44:45], s[40:41] op_sel_hi:[1,1,0]
	v_and_b32_e32 v40, 0x7fffffff, v38
	v_pk_fma_f32 v[44:45], v[42:43], v[44:45], s[74:75] op_sel_hi:[1,1,0]
	v_max_f32_e32 v36, 0, v36
	v_pk_fma_f32 v[44:45], v[42:43], v[44:45], s[76:77] op_sel_hi:[1,1,0]
	v_max_f32_e32 v37, 0, v37
	v_pk_mul_f32 v[44:45], v[44:45], v[44:45]
	v_max_f32_e32 v38, v38, v38
	v_pk_mul_f32 v[44:45], v[44:45], v[44:45]
	v_max_f32_e32 v39, v39, v39
	v_pk_mul_f32 v[44:45], v[44:45], v[44:45]
	v_max_f32_e32 v38, 0, v38
	v_pk_mul_f32 v[44:45], v[44:45], v[44:45]
	v_max_f32_e32 v39, 0, v39
	v_rcp_f32_e32 v44, v44
	v_rcp_f32_e32 v45, v45
	s_nop 0
	v_pk_fma_f32 v[36:37], v[42:43], v[44:45], v[36:37] neg_lo:[1,0,0] neg_hi:[1,0,0]
	v_pk_fma_f32 v[42:43], v[40:41], s[94:95], v[152:153] op_sel_hi:[1,0,0]
	s_nop 0
	v_pk_fma_f32 v[42:43], v[40:41], v[42:43], s[96:97] op_sel_hi:[1,1,0]
	s_nop 0
	v_pk_fma_f32 v[42:43], v[40:41], v[42:43], s[98:99] op_sel_hi:[1,1,0]
	s_nop 0
	v_pk_fma_f32 v[42:43], v[40:41], v[42:43], s[40:41] op_sel_hi:[1,1,0]
	s_nop 0
	v_pk_fma_f32 v[42:43], v[40:41], v[42:43], s[74:75] op_sel_hi:[1,1,0]
	s_nop 0
	v_pk_fma_f32 v[42:43], v[40:41], v[42:43], s[76:77] op_sel_hi:[1,1,0]
	s_nop 0
	v_pk_mul_f32 v[42:43], v[42:43], v[42:43]
	s_nop 0
	v_pk_mul_f32 v[42:43], v[42:43], v[42:43]
	s_nop 0
	v_pk_mul_f32 v[42:43], v[42:43], v[42:43]
	s_nop 0
	v_pk_mul_f32 v[42:43], v[42:43], v[42:43]
	s_nop 0
	v_rcp_f32_e32 v42, v42
	v_rcp_f32_e32 v43, v43
	s_nop 0
	v_pk_fma_f32 v[38:39], v[40:41], v[42:43], v[38:39] neg_lo:[1,0,0] neg_hi:[1,0,0]
	v_and_b32_e32 v43, 0x7fffffff, v33
	v_and_b32_e32 v42, 0x7fffffff, v32
	v_pk_fma_f32 v[44:45], v[42:43], s[94:95], v[152:153] op_sel_hi:[1,0,0]
	v_max_f32_e32 v32, v32, v32
	v_pk_fma_f32 v[44:45], v[42:43], v[44:45], s[96:97] op_sel_hi:[1,1,0]
	v_max_f32_e32 v33, v33, v33
	v_pk_fma_f32 v[44:45], v[42:43], v[44:45], s[98:99] op_sel_hi:[1,1,0]
	v_and_b32_e32 v41, 0x7fffffff, v35
	v_pk_fma_f32 v[44:45], v[42:43], v[44:45], s[40:41] op_sel_hi:[1,1,0]
	v_and_b32_e32 v40, 0x7fffffff, v34
	v_pk_fma_f32 v[44:45], v[42:43], v[44:45], s[74:75] op_sel_hi:[1,1,0]
	v_max_f32_e32 v32, 0, v32
	v_pk_fma_f32 v[44:45], v[42:43], v[44:45], s[76:77] op_sel_hi:[1,1,0]
	v_max_f32_e32 v33, 0, v33
	v_pk_mul_f32 v[44:45], v[44:45], v[44:45]
	v_max_f32_e32 v34, v34, v34
	v_pk_mul_f32 v[44:45], v[44:45], v[44:45]
	v_max_f32_e32 v35, v35, v35
	v_pk_mul_f32 v[44:45], v[44:45], v[44:45]
	v_max_f32_e32 v34, 0, v34
	v_pk_mul_f32 v[44:45], v[44:45], v[44:45]
	v_max_f32_e32 v35, 0, v35
	v_rcp_f32_e32 v44, v44
	v_rcp_f32_e32 v45, v45
	v_pk_fma_f32 v[48:49], v[38:39], v[38:39], v[68:69]
	v_pk_fma_f32 v[42:43], v[42:43], v[44:45], v[32:33] neg_lo:[1,0,0] neg_hi:[1,0,0]
	v_pk_fma_f32 v[32:33], v[40:41], s[94:95], v[152:153] op_sel_hi:[1,0,0]
	v_pk_fma_f32 v[44:45], v[36:37], v[36:37], v[64:65]
	v_pk_fma_f32 v[32:33], v[40:41], v[32:33], s[96:97] op_sel_hi:[1,1,0]
	v_pk_fma_f32 v[46:47], v[42:43], v[42:43], v[66:67]
	v_pk_fma_f32 v[32:33], v[40:41], v[32:33], s[98:99] op_sel_hi:[1,1,0]
	s_nop 0
	v_pk_fma_f32 v[32:33], v[40:41], v[32:33], s[40:41] op_sel_hi:[1,1,0]
	s_nop 0
	v_pk_fma_f32 v[32:33], v[40:41], v[32:33], s[74:75] op_sel_hi:[1,1,0]
	s_nop 0
	v_pk_fma_f32 v[32:33], v[40:41], v[32:33], s[76:77] op_sel_hi:[1,1,0]
	s_nop 0
	v_pk_mul_f32 v[32:33], v[32:33], v[32:33]
	s_nop 0
	v_pk_mul_f32 v[32:33], v[32:33], v[32:33]
	s_nop 0
	v_pk_mul_f32 v[32:33], v[32:33], v[32:33]
	s_nop 0
	v_pk_mul_f32 v[32:33], v[32:33], v[32:33]
	s_nop 0
	v_rcp_f32_e32 v32, v32
	v_rcp_f32_e32 v33, v33
	s_nop 0
	v_pk_fma_f32 v[40:41], v[40:41], v[32:33], v[34:35] neg_lo:[1,0,0] neg_hi:[1,0,0]
	v_cvt_pk_bf16_f32 v32, v36, v37
	v_cvt_pk_bf16_f32 v33, v38, v39
	v_cvt_pk_bf16_f32 v34, v42, v43
	s_nop 0
	v_cvt_pk_bf16_f32 v35, v40, v41
	global_store_dwordx4 v[52:53], v[32:35], off offset:128 nt
	v_pk_fma_f32 v[50:51], v[40:41], v[40:41], v[70:71]
	s_nop 0
	v_and_b32_e32 v35, 0x7fffffff, v29
	v_and_b32_e32 v34, 0x7fffffff, v28
	v_pk_fma_f32 v[36:37], v[34:35], s[94:95], v[152:153] op_sel_hi:[1,0,0]
	v_max_f32_e32 v28, v28, v28
	v_pk_fma_f32 v[36:37], v[34:35], v[36:37], s[96:97] op_sel_hi:[1,1,0]
	v_max_f32_e32 v29, v29, v29
	v_pk_fma_f32 v[36:37], v[34:35], v[36:37], s[98:99] op_sel_hi:[1,1,0]
	v_and_b32_e32 v33, 0x7fffffff, v31
	v_pk_fma_f32 v[36:37], v[34:35], v[36:37], s[40:41] op_sel_hi:[1,1,0]
	v_and_b32_e32 v32, 0x7fffffff, v30
	v_pk_fma_f32 v[36:37], v[34:35], v[36:37], s[74:75] op_sel_hi:[1,1,0]
	v_max_f32_e32 v28, 0, v28
	v_pk_fma_f32 v[36:37], v[34:35], v[36:37], s[76:77] op_sel_hi:[1,1,0]
	v_max_f32_e32 v29, 0, v29
	v_pk_mul_f32 v[36:37], v[36:37], v[36:37]
	v_max_f32_e32 v30, v30, v30
	v_pk_mul_f32 v[36:37], v[36:37], v[36:37]
	v_max_f32_e32 v31, v31, v31
	v_pk_mul_f32 v[36:37], v[36:37], v[36:37]
	v_max_f32_e32 v30, 0, v30
	v_pk_mul_f32 v[36:37], v[36:37], v[36:37]
	v_max_f32_e32 v31, 0, v31
	v_rcp_f32_e32 v36, v36
	v_rcp_f32_e32 v37, v37
	s_nop 0
	v_pk_fma_f32 v[34:35], v[34:35], v[36:37], v[28:29] neg_lo:[1,0,0] neg_hi:[1,0,0]
	v_pk_fma_f32 v[28:29], v[32:33], s[94:95], v[152:153] op_sel_hi:[1,0,0]
	s_nop 0
	v_pk_fma_f32 v[28:29], v[32:33], v[28:29], s[96:97] op_sel_hi:[1,1,0]
	s_nop 0
	v_pk_fma_f32 v[28:29], v[32:33], v[28:29], s[98:99] op_sel_hi:[1,1,0]
	s_nop 0
	v_pk_fma_f32 v[28:29], v[32:33], v[28:29], s[40:41] op_sel_hi:[1,1,0]
	s_nop 0
	v_pk_fma_f32 v[28:29], v[32:33], v[28:29], s[74:75] op_sel_hi:[1,1,0]
	s_nop 0
	v_pk_fma_f32 v[28:29], v[32:33], v[28:29], s[76:77] op_sel_hi:[1,1,0]
	s_nop 0
	v_pk_mul_f32 v[28:29], v[28:29], v[28:29]
	s_nop 0
	v_pk_mul_f32 v[28:29], v[28:29], v[28:29]
	s_nop 0
	v_pk_mul_f32 v[28:29], v[28:29], v[28:29]
	s_nop 0
	v_pk_mul_f32 v[28:29], v[28:29], v[28:29]
	s_nop 0
	v_rcp_f32_e32 v28, v28
	v_rcp_f32_e32 v29, v29
	s_nop 0
	v_pk_fma_f32 v[36:37], v[32:33], v[28:29], v[30:31] neg_lo:[1,0,0] neg_hi:[1,0,0]
	v_and_b32_e32 v31, 0x7fffffff, v25
	v_and_b32_e32 v30, 0x7fffffff, v24
	v_pk_fma_f32 v[32:33], v[30:31], s[94:95], v[152:153] op_sel_hi:[1,0,0]
	v_max_f32_e32 v24, v24, v24
	v_pk_fma_f32 v[32:33], v[30:31], v[32:33], s[96:97] op_sel_hi:[1,1,0]
	v_max_f32_e32 v25, v25, v25
	v_pk_fma_f32 v[32:33], v[30:31], v[32:33], s[98:99] op_sel_hi:[1,1,0]
	v_and_b32_e32 v29, 0x7fffffff, v27
	v_pk_fma_f32 v[32:33], v[30:31], v[32:33], s[40:41] op_sel_hi:[1,1,0]
	v_and_b32_e32 v28, 0x7fffffff, v26
	v_pk_fma_f32 v[32:33], v[30:31], v[32:33], s[74:75] op_sel_hi:[1,1,0]
	v_max_f32_e32 v24, 0, v24
	v_pk_fma_f32 v[32:33], v[30:31], v[32:33], s[76:77] op_sel_hi:[1,1,0]
	v_max_f32_e32 v25, 0, v25
	v_pk_mul_f32 v[32:33], v[32:33], v[32:33]
	v_max_f32_e32 v26, v26, v26
	v_pk_mul_f32 v[32:33], v[32:33], v[32:33]
	v_max_f32_e32 v27, v27, v27
	v_pk_mul_f32 v[32:33], v[32:33], v[32:33]
	v_max_f32_e32 v26, 0, v26
	v_pk_mul_f32 v[32:33], v[32:33], v[32:33]
	v_max_f32_e32 v27, 0, v27
	v_rcp_f32_e32 v32, v32
	v_rcp_f32_e32 v33, v33
	s_nop 0
	v_pk_fma_f32 v[38:39], v[30:31], v[32:33], v[24:25] neg_lo:[1,0,0] neg_hi:[1,0,0]
	v_pk_fma_f32 v[24:25], v[28:29], s[94:95], v[152:153] op_sel_hi:[1,0,0]
	v_cvt_pk_bf16_f32 v32, v34, v35
	v_cvt_pk_bf16_f32 v33, v36, v37
	s_nop 0
	v_pk_fma_f32 v[24:25], v[28:29], v[24:25], s[96:97] op_sel_hi:[1,1,0]
	s_nop 0
	v_pk_fma_f32 v[24:25], v[28:29], v[24:25], s[98:99] op_sel_hi:[1,1,0]
	s_nop 0
	v_pk_fma_f32 v[24:25], v[28:29], v[24:25], s[40:41] op_sel_hi:[1,1,0]
	s_nop 0
	v_pk_fma_f32 v[24:25], v[28:29], v[24:25], s[74:75] op_sel_hi:[1,1,0]
	s_nop 0
	v_pk_fma_f32 v[24:25], v[28:29], v[24:25], s[76:77] op_sel_hi:[1,1,0]
	s_nop 0
	v_pk_mul_f32 v[24:25], v[24:25], v[24:25]
	s_nop 0
	v_pk_mul_f32 v[24:25], v[24:25], v[24:25]
	s_nop 0
	v_pk_mul_f32 v[24:25], v[24:25], v[24:25]
	s_nop 0
	v_pk_mul_f32 v[24:25], v[24:25], v[24:25]
	s_nop 0
	v_rcp_f32_e32 v24, v24
	v_rcp_f32_e32 v25, v25
	s_nop 0
	v_pk_fma_f32 v[40:41], v[28:29], v[24:25], v[26:27] neg_lo:[1,0,0] neg_hi:[1,0,0]
	v_pk_fma_f32 v[28:29], v[36:37], v[36:37], v[58:59]
	v_mov_b32_e32 v37, s5
	v_or_b32_e32 v36, s4, v138
	v_lshlrev_b64 v[36:37], 10, v[36:37]
	v_pk_fma_f32 v[24:25], v[34:35], v[34:35], v[54:55]
	v_cvt_pk_bf16_f32 v34, v38, v39
	v_cvt_pk_bf16_f32 v35, v40, v41
	v_lshl_add_u64 v[36:37], v[142:143], 0, v[36:37]
	global_store_dwordx4 v[36:37], v[32:35], off nt
	v_pk_fma_f32 v[26:27], v[38:39], v[38:39], v[56:57]
	v_pk_fma_f32 v[30:31], v[40:41], v[40:41], v[60:61]
	v_and_b32_e32 v35, 0x7fffffff, v21
	v_and_b32_e32 v34, 0x7fffffff, v20
	v_pk_fma_f32 v[38:39], v[34:35], s[94:95], v[152:153] op_sel_hi:[1,0,0]
	v_max_f32_e32 v20, v20, v20
	v_pk_fma_f32 v[38:39], v[34:35], v[38:39], s[96:97] op_sel_hi:[1,1,0]
	v_max_f32_e32 v21, v21, v21
	v_pk_fma_f32 v[38:39], v[34:35], v[38:39], s[98:99] op_sel_hi:[1,1,0]
	v_and_b32_e32 v33, 0x7fffffff, v23
	v_pk_fma_f32 v[38:39], v[34:35], v[38:39], s[40:41] op_sel_hi:[1,1,0]
	v_and_b32_e32 v32, 0x7fffffff, v22
	v_pk_fma_f32 v[38:39], v[34:35], v[38:39], s[74:75] op_sel_hi:[1,1,0]
	v_max_f32_e32 v20, 0, v20
	v_pk_fma_f32 v[38:39], v[34:35], v[38:39], s[76:77] op_sel_hi:[1,1,0]
	v_max_f32_e32 v21, 0, v21
	v_pk_mul_f32 v[38:39], v[38:39], v[38:39]
	v_max_f32_e32 v22, v22, v22
	v_pk_mul_f32 v[38:39], v[38:39], v[38:39]
	v_max_f32_e32 v23, v23, v23
	v_pk_mul_f32 v[38:39], v[38:39], v[38:39]
	v_max_f32_e32 v22, 0, v22
	v_pk_mul_f32 v[38:39], v[38:39], v[38:39]
	v_max_f32_e32 v23, 0, v23
	v_rcp_f32_e32 v38, v38
	v_rcp_f32_e32 v39, v39
	s_nop 0
	v_pk_fma_f32 v[20:21], v[34:35], v[38:39], v[20:21] neg_lo:[1,0,0] neg_hi:[1,0,0]
	v_pk_fma_f32 v[34:35], v[32:33], s[94:95], v[152:153] op_sel_hi:[1,0,0]
	s_nop 0
	v_pk_fma_f32 v[34:35], v[32:33], v[34:35], s[96:97] op_sel_hi:[1,1,0]
	s_nop 0
	v_pk_fma_f32 v[34:35], v[32:33], v[34:35], s[98:99] op_sel_hi:[1,1,0]
	s_nop 0
	v_pk_fma_f32 v[34:35], v[32:33], v[34:35], s[40:41] op_sel_hi:[1,1,0]
	s_nop 0
	v_pk_fma_f32 v[34:35], v[32:33], v[34:35], s[74:75] op_sel_hi:[1,1,0]
	s_nop 0
	v_pk_fma_f32 v[34:35], v[32:33], v[34:35], s[76:77] op_sel_hi:[1,1,0]
	s_nop 0
	v_pk_mul_f32 v[34:35], v[34:35], v[34:35]
	s_nop 0
	v_pk_mul_f32 v[34:35], v[34:35], v[34:35]
	s_nop 0
	v_pk_mul_f32 v[34:35], v[34:35], v[34:35]
	s_nop 0
	v_pk_mul_f32 v[34:35], v[34:35], v[34:35]
	s_nop 0
	v_rcp_f32_e32 v34, v34
	v_rcp_f32_e32 v35, v35
	s_nop 0
	v_pk_fma_f32 v[22:23], v[32:33], v[34:35], v[22:23] neg_lo:[1,0,0] neg_hi:[1,0,0]
	v_and_b32_e32 v35, 0x7fffffff, v17
	v_and_b32_e32 v34, 0x7fffffff, v16
	v_pk_fma_f32 v[38:39], v[34:35], s[94:95], v[152:153] op_sel_hi:[1,0,0]
	v_max_f32_e32 v16, v16, v16
	v_pk_fma_f32 v[38:39], v[34:35], v[38:39], s[96:97] op_sel_hi:[1,1,0]
	v_max_f32_e32 v17, v17, v17
	v_pk_fma_f32 v[38:39], v[34:35], v[38:39], s[98:99] op_sel_hi:[1,1,0]
	v_and_b32_e32 v33, 0x7fffffff, v19
	v_pk_fma_f32 v[38:39], v[34:35], v[38:39], s[40:41] op_sel_hi:[1,1,0]
	v_and_b32_e32 v32, 0x7fffffff, v18
	v_pk_fma_f32 v[38:39], v[34:35], v[38:39], s[74:75] op_sel_hi:[1,1,0]
	v_max_f32_e32 v16, 0, v16
	v_pk_fma_f32 v[38:39], v[34:35], v[38:39], s[76:77] op_sel_hi:[1,1,0]
	v_max_f32_e32 v17, 0, v17
	v_pk_mul_f32 v[38:39], v[38:39], v[38:39]
	v_max_f32_e32 v18, v18, v18
	v_pk_mul_f32 v[38:39], v[38:39], v[38:39]
	v_max_f32_e32 v19, v19, v19
	v_pk_mul_f32 v[38:39], v[38:39], v[38:39]
	v_max_f32_e32 v18, 0, v18
	v_pk_mul_f32 v[38:39], v[38:39], v[38:39]
	v_max_f32_e32 v19, 0, v19
	v_rcp_f32_e32 v38, v38
	v_rcp_f32_e32 v39, v39
	v_pk_fma_f32 v[42:43], v[22:23], v[22:23], v[48:49]
	v_pk_fma_f32 v[34:35], v[34:35], v[38:39], v[16:17] neg_lo:[1,0,0] neg_hi:[1,0,0]
	v_pk_fma_f32 v[16:17], v[32:33], s[94:95], v[152:153] op_sel_hi:[1,0,0]
	v_pk_fma_f32 v[38:39], v[20:21], v[20:21], v[44:45]
	v_pk_fma_f32 v[16:17], v[32:33], v[16:17], s[96:97] op_sel_hi:[1,1,0]
	v_pk_fma_f32 v[40:41], v[34:35], v[34:35], v[46:47]
	v_pk_fma_f32 v[16:17], v[32:33], v[16:17], s[98:99] op_sel_hi:[1,1,0]
	s_nop 0
	v_pk_fma_f32 v[16:17], v[32:33], v[16:17], s[40:41] op_sel_hi:[1,1,0]
	s_nop 0
	v_pk_fma_f32 v[16:17], v[32:33], v[16:17], s[74:75] op_sel_hi:[1,1,0]
	s_nop 0
	v_pk_fma_f32 v[16:17], v[32:33], v[16:17], s[76:77] op_sel_hi:[1,1,0]
	s_nop 0
	v_pk_mul_f32 v[16:17], v[16:17], v[16:17]
	s_nop 0
	v_pk_mul_f32 v[16:17], v[16:17], v[16:17]
	s_nop 0
	v_pk_mul_f32 v[16:17], v[16:17], v[16:17]
	s_nop 0
	v_pk_mul_f32 v[16:17], v[16:17], v[16:17]
	s_nop 0
	v_rcp_f32_e32 v16, v16
	v_rcp_f32_e32 v17, v17
	s_nop 0
	v_pk_fma_f32 v[32:33], v[32:33], v[16:17], v[18:19] neg_lo:[1,0,0] neg_hi:[1,0,0]
	v_cvt_pk_bf16_f32 v16, v20, v21
	v_mov_b32_e32 v21, s1
	v_or_b32_e32 v20, s0, v138
	v_lshlrev_b64 v[20:21], 10, v[20:21]
	v_cvt_pk_bf16_f32 v17, v22, v23
	v_cvt_pk_bf16_f32 v18, v34, v35
	v_cvt_pk_bf16_f32 v19, v32, v33
	v_lshl_add_u64 v[20:21], v[142:143], 0, v[20:21]
	global_store_dwordx4 v[20:21], v[16:19], off nt
	v_readlane_b32 s0, v254, 18
	v_readlane_b32 s1, v254, 19
	v_and_b32_e32 v19, 0x7fffffff, v13
	v_and_b32_e32 v18, 0x7fffffff, v12
	v_pk_fma_f32 v[22:23], v[18:19], s[94:95], v[152:153] op_sel_hi:[1,0,0]
	v_max_f32_e32 v12, v12, v12
	v_pk_fma_f32 v[22:23], v[18:19], v[22:23], s[96:97] op_sel_hi:[1,1,0]
	v_max_f32_e32 v13, v13, v13
	v_pk_fma_f32 v[22:23], v[18:19], v[22:23], s[98:99] op_sel_hi:[1,1,0]
	v_and_b32_e32 v17, 0x7fffffff, v15
	v_pk_fma_f32 v[22:23], v[18:19], v[22:23], s[40:41] op_sel_hi:[1,1,0]
	v_and_b32_e32 v16, 0x7fffffff, v14
	v_pk_fma_f32 v[22:23], v[18:19], v[22:23], s[74:75] op_sel_hi:[1,1,0]
	v_max_f32_e32 v12, 0, v12
	v_pk_fma_f32 v[22:23], v[18:19], v[22:23], s[76:77] op_sel_hi:[1,1,0]
	v_max_f32_e32 v13, 0, v13
	v_pk_mul_f32 v[22:23], v[22:23], v[22:23]
	v_max_f32_e32 v14, v14, v14
	v_pk_mul_f32 v[22:23], v[22:23], v[22:23]
	v_max_f32_e32 v15, v15, v15
	v_pk_mul_f32 v[22:23], v[22:23], v[22:23]
	v_max_f32_e32 v14, 0, v14
	v_pk_mul_f32 v[22:23], v[22:23], v[22:23]
	v_max_f32_e32 v15, 0, v15
	v_rcp_f32_e32 v22, v22
	v_rcp_f32_e32 v23, v23
	v_pk_fma_f32 v[44:45], v[32:33], v[32:33], v[50:51]
	v_pk_fma_f32 v[12:13], v[18:19], v[22:23], v[12:13] neg_lo:[1,0,0] neg_hi:[1,0,0]
	v_pk_fma_f32 v[18:19], v[16:17], s[94:95], v[152:153] op_sel_hi:[1,0,0]
	s_nop 0
	v_pk_fma_f32 v[18:19], v[16:17], v[18:19], s[96:97] op_sel_hi:[1,1,0]
	s_nop 0
	v_pk_fma_f32 v[18:19], v[16:17], v[18:19], s[98:99] op_sel_hi:[1,1,0]
	s_nop 0
	v_pk_fma_f32 v[18:19], v[16:17], v[18:19], s[40:41] op_sel_hi:[1,1,0]
	s_nop 0
	v_pk_fma_f32 v[18:19], v[16:17], v[18:19], s[74:75] op_sel_hi:[1,1,0]
	s_nop 0
	v_pk_fma_f32 v[18:19], v[16:17], v[18:19], s[76:77] op_sel_hi:[1,1,0]
	s_nop 0
	v_pk_mul_f32 v[18:19], v[18:19], v[18:19]
	s_nop 0
	v_pk_mul_f32 v[18:19], v[18:19], v[18:19]
	s_nop 0
	v_pk_mul_f32 v[18:19], v[18:19], v[18:19]
	s_nop 0
	v_pk_mul_f32 v[18:19], v[18:19], v[18:19]
	s_nop 0
	v_rcp_f32_e32 v18, v18
	v_rcp_f32_e32 v19, v19
	s_nop 0
	v_pk_fma_f32 v[14:15], v[16:17], v[18:19], v[14:15] neg_lo:[1,0,0] neg_hi:[1,0,0]
	v_and_b32_e32 v19, 0x7fffffff, v9
	v_and_b32_e32 v18, 0x7fffffff, v8
	v_pk_fma_f32 v[22:23], v[18:19], s[94:95], v[152:153] op_sel_hi:[1,0,0]
	v_max_f32_e32 v8, v8, v8
	v_pk_fma_f32 v[22:23], v[18:19], v[22:23], s[96:97] op_sel_hi:[1,1,0]
	v_max_f32_e32 v9, v9, v9
	v_pk_fma_f32 v[22:23], v[18:19], v[22:23], s[98:99] op_sel_hi:[1,1,0]
	v_and_b32_e32 v17, 0x7fffffff, v11
	v_pk_fma_f32 v[22:23], v[18:19], v[22:23], s[40:41] op_sel_hi:[1,1,0]
	v_and_b32_e32 v16, 0x7fffffff, v10
	v_pk_fma_f32 v[22:23], v[18:19], v[22:23], s[74:75] op_sel_hi:[1,1,0]
	v_max_f32_e32 v8, 0, v8
	v_pk_fma_f32 v[22:23], v[18:19], v[22:23], s[76:77] op_sel_hi:[1,1,0]
	v_max_f32_e32 v9, 0, v9
	v_pk_mul_f32 v[22:23], v[22:23], v[22:23]
	v_max_f32_e32 v10, v10, v10
	v_pk_mul_f32 v[22:23], v[22:23], v[22:23]
	v_max_f32_e32 v11, v11, v11
	v_pk_mul_f32 v[22:23], v[22:23], v[22:23]
	v_max_f32_e32 v10, 0, v10
	v_pk_mul_f32 v[22:23], v[22:23], v[22:23]
	v_max_f32_e32 v11, 0, v11
	v_rcp_f32_e32 v22, v22
	v_rcp_f32_e32 v23, v23
	s_nop 0
	v_pk_fma_f32 v[18:19], v[18:19], v[22:23], v[8:9] neg_lo:[1,0,0] neg_hi:[1,0,0]
	v_pk_fma_f32 v[8:9], v[16:17], s[94:95], v[152:153] op_sel_hi:[1,0,0]
	v_pk_fma_f32 v[22:23], v[12:13], v[12:13], v[24:25]
	v_pk_fma_f32 v[8:9], v[16:17], v[8:9], s[96:97] op_sel_hi:[1,1,0]
	v_pk_fma_f32 v[24:25], v[18:19], v[18:19], v[26:27]
	v_pk_fma_f32 v[8:9], v[16:17], v[8:9], s[98:99] op_sel_hi:[1,1,0]
	v_pk_fma_f32 v[26:27], v[14:15], v[14:15], v[28:29]
	v_pk_fma_f32 v[8:9], v[16:17], v[8:9], s[40:41] op_sel_hi:[1,1,0]
	s_nop 0
	v_pk_fma_f32 v[8:9], v[16:17], v[8:9], s[74:75] op_sel_hi:[1,1,0]
	s_nop 0
	v_pk_fma_f32 v[8:9], v[16:17], v[8:9], s[76:77] op_sel_hi:[1,1,0]
	s_nop 0
	v_pk_mul_f32 v[8:9], v[8:9], v[8:9]
	s_nop 0
	v_pk_mul_f32 v[8:9], v[8:9], v[8:9]
	s_nop 0
	v_pk_mul_f32 v[8:9], v[8:9], v[8:9]
	s_nop 0
	v_pk_mul_f32 v[8:9], v[8:9], v[8:9]
	s_nop 0
	v_rcp_f32_e32 v8, v8
	v_rcp_f32_e32 v9, v9
	s_nop 0
	v_pk_fma_f32 v[16:17], v[16:17], v[8:9], v[10:11] neg_lo:[1,0,0] neg_hi:[1,0,0]
	v_cvt_pk_bf16_f32 v8, v12, v13
	v_cvt_pk_bf16_f32 v9, v14, v15
	v_cvt_pk_bf16_f32 v10, v18, v19
	s_nop 0
	v_cvt_pk_bf16_f32 v11, v16, v17
	global_store_dwordx4 v[36:37], v[8:11], off offset:128 nt
	v_pk_fma_f32 v[28:29], v[16:17], v[16:17], v[30:31]
	s_nop 0
	v_and_b32_e32 v11, 0x7fffffff, v5
	v_and_b32_e32 v10, 0x7fffffff, v4
	v_pk_fma_f32 v[12:13], v[10:11], s[94:95], v[152:153] op_sel_hi:[1,0,0]
	v_max_f32_e32 v4, v4, v4
	v_pk_fma_f32 v[12:13], v[10:11], v[12:13], s[96:97] op_sel_hi:[1,1,0]
	v_max_f32_e32 v5, v5, v5
	v_pk_fma_f32 v[12:13], v[10:11], v[12:13], s[98:99] op_sel_hi:[1,1,0]
	v_and_b32_e32 v9, 0x7fffffff, v7
	v_pk_fma_f32 v[12:13], v[10:11], v[12:13], s[40:41] op_sel_hi:[1,1,0]
	v_and_b32_e32 v8, 0x7fffffff, v6
	v_pk_fma_f32 v[12:13], v[10:11], v[12:13], s[74:75] op_sel_hi:[1,1,0]
	v_max_f32_e32 v4, 0, v4
	v_pk_fma_f32 v[12:13], v[10:11], v[12:13], s[76:77] op_sel_hi:[1,1,0]
	v_max_f32_e32 v5, 0, v5
	v_pk_mul_f32 v[12:13], v[12:13], v[12:13]
	v_max_f32_e32 v6, v6, v6
	v_pk_mul_f32 v[12:13], v[12:13], v[12:13]
	v_max_f32_e32 v7, v7, v7
	v_pk_mul_f32 v[12:13], v[12:13], v[12:13]
	v_max_f32_e32 v6, 0, v6
	v_pk_mul_f32 v[12:13], v[12:13], v[12:13]
	v_max_f32_e32 v7, 0, v7
	v_rcp_f32_e32 v12, v12
	v_rcp_f32_e32 v13, v13
	s_nop 0
	v_pk_fma_f32 v[4:5], v[10:11], v[12:13], v[4:5] neg_lo:[1,0,0] neg_hi:[1,0,0]
	v_pk_fma_f32 v[10:11], v[8:9], s[94:95], v[152:153] op_sel_hi:[1,0,0]
	s_nop 0
	v_pk_fma_f32 v[10:11], v[8:9], v[10:11], s[96:97] op_sel_hi:[1,1,0]
	s_nop 0
	v_pk_fma_f32 v[10:11], v[8:9], v[10:11], s[98:99] op_sel_hi:[1,1,0]
	s_nop 0
	v_pk_fma_f32 v[10:11], v[8:9], v[10:11], s[40:41] op_sel_hi:[1,1,0]
	s_nop 0
	v_pk_fma_f32 v[10:11], v[8:9], v[10:11], s[74:75] op_sel_hi:[1,1,0]
	s_nop 0
	v_pk_fma_f32 v[10:11], v[8:9], v[10:11], s[76:77] op_sel_hi:[1,1,0]
	s_nop 0
	v_pk_mul_f32 v[10:11], v[10:11], v[10:11]
	s_nop 0
	v_pk_mul_f32 v[10:11], v[10:11], v[10:11]
	s_nop 0
	v_pk_mul_f32 v[10:11], v[10:11], v[10:11]
	s_nop 0
	v_pk_mul_f32 v[10:11], v[10:11], v[10:11]
	s_nop 0
	v_rcp_f32_e32 v10, v10
	v_rcp_f32_e32 v11, v11
	s_nop 0
	v_pk_fma_f32 v[6:7], v[8:9], v[10:11], v[6:7] neg_lo:[1,0,0] neg_hi:[1,0,0]
	v_and_b32_e32 v11, 0x7fffffff, v1
	v_and_b32_e32 v10, 0x7fffffff, v0
	v_pk_fma_f32 v[12:13], v[10:11], s[94:95], v[152:153] op_sel_hi:[1,0,0]
	v_max_f32_e32 v0, v0, v0
	v_pk_fma_f32 v[12:13], v[10:11], v[12:13], s[96:97] op_sel_hi:[1,1,0]
	v_max_f32_e32 v1, v1, v1
	v_pk_fma_f32 v[12:13], v[10:11], v[12:13], s[98:99] op_sel_hi:[1,1,0]
	v_and_b32_e32 v9, 0x7fffffff, v3
	v_pk_fma_f32 v[12:13], v[10:11], v[12:13], s[40:41] op_sel_hi:[1,1,0]
	v_and_b32_e32 v8, 0x7fffffff, v2
	v_pk_fma_f32 v[12:13], v[10:11], v[12:13], s[74:75] op_sel_hi:[1,1,0]
	v_max_f32_e32 v0, 0, v0
	v_pk_fma_f32 v[12:13], v[10:11], v[12:13], s[76:77] op_sel_hi:[1,1,0]
	v_max_f32_e32 v1, 0, v1
	v_pk_mul_f32 v[12:13], v[12:13], v[12:13]
	v_max_f32_e32 v2, v2, v2
	v_pk_mul_f32 v[12:13], v[12:13], v[12:13]
	v_max_f32_e32 v3, v3, v3
	v_pk_mul_f32 v[12:13], v[12:13], v[12:13]
	v_max_f32_e32 v2, 0, v2
	v_pk_mul_f32 v[12:13], v[12:13], v[12:13]
	v_max_f32_e32 v3, 0, v3
	v_rcp_f32_e32 v12, v12
	v_rcp_f32_e32 v13, v13
	v_pk_fma_f32 v[16:17], v[6:7], v[6:7], v[42:43]
	v_pk_fma_f32 v[10:11], v[10:11], v[12:13], v[0:1] neg_lo:[1,0,0] neg_hi:[1,0,0]
	v_pk_fma_f32 v[0:1], v[8:9], s[94:95], v[152:153] op_sel_hi:[1,0,0]
	v_pk_fma_f32 v[12:13], v[4:5], v[4:5], v[38:39]
	v_pk_fma_f32 v[0:1], v[8:9], v[0:1], s[96:97] op_sel_hi:[1,1,0]
	v_pk_fma_f32 v[14:15], v[10:11], v[10:11], v[40:41]
	v_pk_fma_f32 v[0:1], v[8:9], v[0:1], s[98:99] op_sel_hi:[1,1,0]
	s_nop 0
	v_pk_fma_f32 v[0:1], v[8:9], v[0:1], s[40:41] op_sel_hi:[1,1,0]
	s_nop 0
	v_pk_fma_f32 v[0:1], v[8:9], v[0:1], s[74:75] op_sel_hi:[1,1,0]
	s_nop 0
	v_pk_fma_f32 v[0:1], v[8:9], v[0:1], s[76:77] op_sel_hi:[1,1,0]
	s_nop 0
	v_pk_mul_f32 v[0:1], v[0:1], v[0:1]
	s_nop 0
	v_pk_mul_f32 v[0:1], v[0:1], v[0:1]
	s_nop 0
	v_pk_mul_f32 v[0:1], v[0:1], v[0:1]
	s_nop 0
	v_pk_mul_f32 v[0:1], v[0:1], v[0:1]
	s_nop 0
	v_rcp_f32_e32 v0, v0
	v_rcp_f32_e32 v1, v1
	s_nop 0
	v_pk_fma_f32 v[8:9], v[8:9], v[0:1], v[2:3] neg_lo:[1,0,0] neg_hi:[1,0,0]
	v_cvt_pk_bf16_f32 v0, v4, v5
	v_cvt_pk_bf16_f32 v1, v6, v7
	v_cvt_pk_bf16_f32 v2, v10, v11
	s_nop 0
	v_cvt_pk_bf16_f32 v3, v8, v9
	global_store_dwordx4 v[20:21], v[0:3], off offset:128 nt
	v_pk_fma_f32 v[18:19], v[8:9], v[8:9], v[44:45]
	s_nop 0
	v_add_f32_dpp v0, v22, v22 row_ror:8 row_mask:0xf bank_mask:0xf bound_ctrl:1
	v_add_f32_dpp v1, v23, v23 row_ror:8 row_mask:0xf bank_mask:0xf bound_ctrl:1
	s_nop 0
	v_add_f32_dpp v0, v0, v0 row_ror:4 row_mask:0xf bank_mask:0xf bound_ctrl:1
	v_add_f32_dpp v1, v1, v1 row_ror:4 row_mask:0xf bank_mask:0xf bound_ctrl:1
	s_nop 0
	v_add_f32_dpp v0, v0, v0 row_ror:2 row_mask:0xf bank_mask:0xf bound_ctrl:1
	v_add_f32_dpp v1, v1, v1 row_ror:2 row_mask:0xf bank_mask:0xf bound_ctrl:1
	s_nop 0
	v_add_f32_dpp v0, v0, v0 row_ror:1 row_mask:0xf bank_mask:0xf bound_ctrl:1
	v_cndmask_b32_e64 v0, 0, v0, s[0:1]
	v_readlane_b32 s0, v254, 20
	v_add_f32_dpp v1, v1, v1 row_ror:1 row_mask:0xf bank_mask:0xf bound_ctrl:1
	v_readlane_b32 s1, v254, 21
	s_nop 1
	v_cndmask_b32_e64 v0, v0, v1, s[0:1]
	v_add_f32_dpp v1, v26, v26 row_ror:8 row_mask:0xf bank_mask:0xf bound_ctrl:1
	v_readlane_b32 s0, v254, 22
	v_readlane_b32 s1, v254, 23
	v_add_f32_dpp v1, v1, v1 row_ror:4 row_mask:0xf bank_mask:0xf bound_ctrl:1
	s_nop 1
	v_add_f32_dpp v1, v1, v1 row_ror:2 row_mask:0xf bank_mask:0xf bound_ctrl:1
	s_nop 1
	v_add_f32_dpp v1, v1, v1 row_ror:1 row_mask:0xf bank_mask:0xf bound_ctrl:1
	v_cndmask_b32_e64 v0, v0, v1, s[0:1]
	v_readlane_b32 s0, v254, 24
	v_add_f32_dpp v1, v27, v27 row_ror:8 row_mask:0xf bank_mask:0xf bound_ctrl:1
	v_readlane_b32 s1, v254, 25
	s_nop 0
	v_add_f32_dpp v1, v1, v1 row_ror:4 row_mask:0xf bank_mask:0xf bound_ctrl:1
	s_nop 1
	v_add_f32_dpp v1, v1, v1 row_ror:2 row_mask:0xf bank_mask:0xf bound_ctrl:1
	s_nop 1
	v_add_f32_dpp v1, v1, v1 row_ror:1 row_mask:0xf bank_mask:0xf bound_ctrl:1
	v_cndmask_b32_e64 v0, v0, v1, s[0:1]
	v_readlane_b32 s0, v254, 26
	v_add_f32_dpp v1, v24, v24 row_ror:8 row_mask:0xf bank_mask:0xf bound_ctrl:1
	v_readlane_b32 s1, v254, 27
	s_nop 0
	v_add_f32_dpp v1, v1, v1 row_ror:4 row_mask:0xf bank_mask:0xf bound_ctrl:1
	s_nop 1
	v_add_f32_dpp v1, v1, v1 row_ror:2 row_mask:0xf bank_mask:0xf bound_ctrl:1
	s_nop 1
	v_add_f32_dpp v1, v1, v1 row_ror:1 row_mask:0xf bank_mask:0xf bound_ctrl:1
	v_cndmask_b32_e64 v0, v0, v1, s[0:1]
	v_readlane_b32 s0, v254, 28
	v_add_f32_dpp v1, v25, v25 row_ror:8 row_mask:0xf bank_mask:0xf bound_ctrl:1
	v_readlane_b32 s1, v254, 29
	s_nop 0
	v_add_f32_dpp v1, v1, v1 row_ror:4 row_mask:0xf bank_mask:0xf bound_ctrl:1
	s_nop 1
	v_add_f32_dpp v1, v1, v1 row_ror:2 row_mask:0xf bank_mask:0xf bound_ctrl:1
	s_nop 1
	v_add_f32_dpp v1, v1, v1 row_ror:1 row_mask:0xf bank_mask:0xf bound_ctrl:1
	v_cndmask_b32_e64 v0, v0, v1, s[0:1]
	v_readlane_b32 s0, v254, 30
	v_add_f32_dpp v1, v28, v28 row_ror:8 row_mask:0xf bank_mask:0xf bound_ctrl:1
	v_readlane_b32 s1, v254, 31
	s_nop 0
	v_add_f32_dpp v1, v1, v1 row_ror:4 row_mask:0xf bank_mask:0xf bound_ctrl:1
	s_nop 1
	v_add_f32_dpp v1, v1, v1 row_ror:2 row_mask:0xf bank_mask:0xf bound_ctrl:1
	s_nop 1
	v_add_f32_dpp v1, v1, v1 row_ror:1 row_mask:0xf bank_mask:0xf bound_ctrl:1
	v_cndmask_b32_e64 v0, v0, v1, s[0:1]
	s_nop 0
	v_add_f32_dpp v1, v29, v29 row_ror:8 row_mask:0xf bank_mask:0xf bound_ctrl:1
	s_nop 1
	v_add_f32_dpp v1, v1, v1 row_ror:4 row_mask:0xf bank_mask:0xf bound_ctrl:1
	s_nop 1
	v_add_f32_dpp v1, v1, v1 row_ror:2 row_mask:0xf bank_mask:0xf bound_ctrl:1
	s_nop 1
	v_add_f32_dpp v1, v1, v1 row_ror:1 row_mask:0xf bank_mask:0xf bound_ctrl:1
	v_cndmask_b32_e64 v0, v0, v1, s[16:17]
	s_nop 0
	v_add_f32_dpp v1, v12, v12 row_ror:8 row_mask:0xf bank_mask:0xf bound_ctrl:1
	s_nop 1
	v_add_f32_dpp v1, v1, v1 row_ror:4 row_mask:0xf bank_mask:0xf bound_ctrl:1
	s_nop 1
	v_add_f32_dpp v1, v1, v1 row_ror:2 row_mask:0xf bank_mask:0xf bound_ctrl:1
	s_nop 1
	v_add_f32_dpp v1, v1, v1 row_ror:1 row_mask:0xf bank_mask:0xf bound_ctrl:1
	v_cndmask_b32_e64 v0, v0, v1, s[18:19]
	s_nop 0
	v_add_f32_dpp v1, v13, v13 row_ror:8 row_mask:0xf bank_mask:0xf bound_ctrl:1
	s_nop 1
	v_add_f32_dpp v1, v1, v1 row_ror:4 row_mask:0xf bank_mask:0xf bound_ctrl:1
	s_nop 1
	v_add_f32_dpp v1, v1, v1 row_ror:2 row_mask:0xf bank_mask:0xf bound_ctrl:1
	s_nop 1
	v_add_f32_dpp v1, v1, v1 row_ror:1 row_mask:0xf bank_mask:0xf bound_ctrl:1
	v_cndmask_b32_e64 v0, v0, v1, s[20:21]
	s_nop 0
	v_add_f32_dpp v1, v16, v16 row_ror:8 row_mask:0xf bank_mask:0xf bound_ctrl:1
	s_nop 1
	v_add_f32_dpp v1, v1, v1 row_ror:4 row_mask:0xf bank_mask:0xf bound_ctrl:1
	s_nop 1
	v_add_f32_dpp v1, v1, v1 row_ror:2 row_mask:0xf bank_mask:0xf bound_ctrl:1
	s_nop 1
	v_add_f32_dpp v1, v1, v1 row_ror:1 row_mask:0xf bank_mask:0xf bound_ctrl:1
	v_cndmask_b32_e64 v0, v0, v1, s[22:23]
	s_nop 0
	v_add_f32_dpp v1, v17, v17 row_ror:8 row_mask:0xf bank_mask:0xf bound_ctrl:1
	s_nop 1
	v_add_f32_dpp v1, v1, v1 row_ror:4 row_mask:0xf bank_mask:0xf bound_ctrl:1
	s_nop 1
	v_add_f32_dpp v1, v1, v1 row_ror:2 row_mask:0xf bank_mask:0xf bound_ctrl:1
	s_nop 1
	v_add_f32_dpp v1, v1, v1 row_ror:1 row_mask:0xf bank_mask:0xf bound_ctrl:1
	v_cndmask_b32_e64 v0, v0, v1, s[24:25]
	s_nop 0
	v_add_f32_dpp v1, v14, v14 row_ror:8 row_mask:0xf bank_mask:0xf bound_ctrl:1
	s_nop 1
	v_add_f32_dpp v1, v1, v1 row_ror:4 row_mask:0xf bank_mask:0xf bound_ctrl:1
	s_nop 1
	v_add_f32_dpp v1, v1, v1 row_ror:2 row_mask:0xf bank_mask:0xf bound_ctrl:1
	s_nop 1
	v_add_f32_dpp v1, v1, v1 row_ror:1 row_mask:0xf bank_mask:0xf bound_ctrl:1
	v_cndmask_b32_e64 v0, v0, v1, s[26:27]
	s_nop 0
	v_add_f32_dpp v1, v15, v15 row_ror:8 row_mask:0xf bank_mask:0xf bound_ctrl:1
	s_nop 1
	v_add_f32_dpp v1, v1, v1 row_ror:4 row_mask:0xf bank_mask:0xf bound_ctrl:1
	s_nop 1
	v_add_f32_dpp v1, v1, v1 row_ror:2 row_mask:0xf bank_mask:0xf bound_ctrl:1
	s_nop 1
	v_add_f32_dpp v1, v1, v1 row_ror:1 row_mask:0xf bank_mask:0xf bound_ctrl:1
	v_cndmask_b32_e64 v0, v0, v1, s[28:29]
	s_nop 0
	v_add_f32_dpp v1, v18, v18 row_ror:8 row_mask:0xf bank_mask:0xf bound_ctrl:1
	s_nop 1
	v_add_f32_dpp v1, v1, v1 row_ror:4 row_mask:0xf bank_mask:0xf bound_ctrl:1
	s_nop 1
	v_add_f32_dpp v1, v1, v1 row_ror:2 row_mask:0xf bank_mask:0xf bound_ctrl:1
	s_nop 1
	v_add_f32_dpp v1, v1, v1 row_ror:1 row_mask:0xf bank_mask:0xf bound_ctrl:1
	v_cndmask_b32_e64 v0, v0, v1, s[30:31]
	s_nop 0
	v_add_f32_dpp v1, v19, v19 row_ror:8 row_mask:0xf bank_mask:0xf bound_ctrl:1
	s_nop 1
	v_add_f32_dpp v1, v1, v1 row_ror:4 row_mask:0xf bank_mask:0xf bound_ctrl:1
	s_nop 1
	v_add_f32_dpp v1, v1, v1 row_ror:2 row_mask:0xf bank_mask:0xf bound_ctrl:1
	s_nop 1
	v_add_f32_dpp v1, v1, v1 row_ror:1 row_mask:0xf bank_mask:0xf bound_ctrl:1
	v_cndmask_b32_e64 v0, v0, v1, s[34:35]
	s_cbranch_vccnz .LBB0_188
	ds_write_b32 v158, v0
